# v18 + nt on the RWKV prep phase scan-input stores
# speedup vs baseline: 1.0067x; 1.0067x over previous
; __device__ __forceinline__ void phase2_main(const Params& p) {
;     ...
;     for (int g = slot; g < NB * 514; g += nslot) {
;         const int ub = g / 514, ui = g - ub * 514, row0 = ub * TP + ui * 16;
;         {
;             const int half = lane >> 5, pc = (lane & 31) * 8;
;             const float sA = pc < 64 ? 2.f : 1.f, sC = pc < 64 ? -1.f : 0.f;
;             const bool lin = pc >= 64 && pc < 128;
;             const f32x4 mA = *(const f32x4*)(mu + 1536 + pc), mB = *(const f32x4*)(mu + 1536 + pc + 4);
;             h16x8 c[8], pv[8];
; #pragma unroll
;             for (int q = 0; q < 8; ++q) {
;                 const int rowa = row0 + 2 * q + half, ta = rowa % TP;
;                 const _Float16* cur = urw + (size_t)rowa * RWS + 1536 + pc;
;                 c[q] = *(const h16x8*)cur;
;                 pv[q] = *(const h16x8*)(ta > 0 ? cur - RWS : cur);
;             }
.LBB0_572:
	v_and_b32_e32 v9, 64, v109
	v_mul_hi_i32 v8, v79, s37
	v_add_u32_e32 v9, 64, v9
	v_xor_b32_e32 v10, 32, v109
	v_lshrrev_b32_e32 v11, 31, v8
	v_ashrrev_i32_e32 v8, 8, v8
	v_cmp_lt_i32_e64 s[0:1], v110, v9
	v_add_u32_e32 v8, v8, v11
	global_load_dwordx4 v[0:3], v[76:77], off offset:16
	global_load_dwordx4 v[4:7], v[76:77], off
	v_cndmask_b32_e64 v11, v109, v110, s[0:1]
	v_cmp_lt_i32_e64 s[0:1], v10, v9
	v_lshlrev_b32_e32 v112, 2, v11
	s_nop 0
	v_cndmask_b32_e64 v9, v109, v10, s[0:1]
	v_mad_i32_i24 v10, v8, s40, v79
	v_mul_i32_i24_e32 v8, 0x2080, v8
	v_lshl_add_u32 v113, v10, 4, v8
	v_or_b32_e32 v42, v113, v104
	v_mul_hi_i32 v8, v42, s41
	v_lshlrev_b32_e32 v111, 2, v9
	v_or_b32_e32 v58, 2, v42
	v_or_b32_e32 v59, 4, v42
	v_or_b32_e32 v60, 6, v42
	v_or_b32_e32 v61, 8, v42
	v_or_b32_e32 v62, 10, v42
	v_or_b32_e32 v63, 12, v42
	v_or_b32_e32 v64, 14, v42
	v_lshrrev_b32_e32 v9, 31, v8
	v_ashrrev_i32_e32 v8, 12, v8
	v_mul_hi_i32 v10, v58, s41
	v_mul_hi_i32 v11, v59, s41
	v_mul_hi_i32 v12, v60, s41
	v_mul_hi_i32 v13, v61, s41
	v_mul_hi_i32 v14, v62, s41
	v_mul_hi_i32 v15, v63, s41
	v_mul_hi_i32 v43, v64, s41
	v_add_u32_e32 v65, v8, v9
	v_lshrrev_b32_e32 v66, 31, v10
	v_ashrrev_i32_e32 v67, 12, v10
	v_lshrrev_b32_e32 v68, 31, v11
	v_ashrrev_i32_e32 v69, 12, v11
	v_lshrrev_b32_e32 v70, 31, v12
	v_ashrrev_i32_e32 v71, 12, v12
	v_lshrrev_b32_e32 v114, 31, v13
	v_ashrrev_i32_e32 v115, 12, v13
	v_lshrrev_b32_e32 v116, 31, v14
	v_ashrrev_i32_e32 v117, 12, v14
	v_lshrrev_b32_e32 v118, 31, v15
	v_ashrrev_i32_e32 v119, 12, v15
	v_lshrrev_b32_e32 v120, 31, v43
	v_ashrrev_i32_e32 v43, 12, v43
	v_mul_i32_i24_e32 v65, 0x2080, v65
	v_mad_i64_i32 v[40:41], s[0:1], v42, s42, v[100:101]
	v_add_u32_e32 v66, v67, v66
	v_add_u32_e32 v67, v69, v68
	v_add_u32_e32 v68, v71, v70
	v_add_u32_e32 v69, v115, v114
	v_add_u32_e32 v70, v117, v116
	v_add_u32_e32 v71, v119, v118
	v_add_u32_e32 v43, v43, v120
	v_sub_u32_e32 v42, v42, v65
	v_mul_i32_i24_e32 v65, 0x2080, v66
	v_mul_i32_i24_e32 v66, 0x2080, v67
	v_mul_i32_i24_e32 v67, 0x2080, v68
	v_mul_i32_i24_e32 v68, 0x2080, v69
	v_mul_i32_i24_e32 v69, 0x2080, v70
	v_mul_i32_i24_e32 v70, 0x2080, v71
	v_mul_i32_i24_e32 v71, 0x2080, v43
	v_cmp_lt_i32_e64 s[14:15], 0, v42
	v_mad_i64_i32 v[44:45], s[0:1], v58, s42, v[100:101]
	v_mad_i64_i32 v[46:47], s[0:1], v59, s42, v[100:101]
	v_mad_i64_i32 v[48:49], s[0:1], v60, s42, v[100:101]
	v_mad_i64_i32 v[50:51], s[0:1], v61, s42, v[100:101]
	v_mad_i64_i32 v[52:53], s[0:1], v62, s42, v[100:101]
	v_mad_i64_i32 v[54:55], s[0:1], v63, s42, v[100:101]
	v_mad_i64_i32 v[56:57], s[0:1], v64, s42, v[100:101]
	v_cndmask_b32_e64 v43, 0, -1, s[14:15]
	v_sub_u32_e32 v58, v58, v65
	v_sub_u32_e32 v65, v59, v66
	v_sub_u32_e32 v60, v60, v67
	v_sub_u32_e32 v66, v61, v68
	v_sub_u32_e32 v62, v62, v69
	v_sub_u32_e32 v68, v63, v70
	v_sub_u32_e32 v64, v64, v71
	v_cndmask_b32_e64 v42, 0, v108, s[14:15]
	global_load_dwordx4 v[36:39], v[40:41], off offset:3072
	global_load_dwordx4 v[32:35], v[44:45], off offset:3072
	v_cmp_lt_i32_e64 s[0:1], 0, v58
	v_cmp_lt_i32_e64 s[12:13], 0, v65
	v_cmp_lt_i32_e64 s[10:11], 0, v60
	v_cmp_lt_i32_e64 s[8:9], 0, v66
	v_cmp_lt_i32_e64 s[6:7], 0, v62
	v_cmp_lt_i32_e64 s[4:5], 0, v68
	v_cmp_lt_i32_e64 s[16:17], 0, v64
	v_lshl_add_u64 v[40:41], v[40:41], 0, v[42:43]
	global_load_dwordx4 v[28:31], v[46:47], off offset:3072
	global_load_dwordx4 v[16:19], v[52:53], off offset:3072
	global_load_dwordx4 v[12:15], v[54:55], off offset:3072
	global_load_dwordx4 v[8:11], v[56:57], off offset:3072
	v_cndmask_b32_e64 v59, 0, -1, s[0:1]
	v_cndmask_b32_e64 v61, 0, -1, s[12:13]
	v_cndmask_b32_e64 v63, 0, -1, s[10:11]
	v_cndmask_b32_e64 v65, 0, -1, s[8:9]
	v_cndmask_b32_e64 v67, 0, -1, s[6:7]
	v_cndmask_b32_e64 v69, 0, -1, s[4:5]
	v_cndmask_b32_e64 v71, 0, -1, s[16:17]
	v_cndmask_b32_e64 v58, 0, v108, s[0:1]
	v_cndmask_b32_e64 v60, 0, v108, s[12:13]
	v_cndmask_b32_e64 v62, 0, v108, s[10:11]
	v_cndmask_b32_e64 v64, 0, v108, s[8:9]
	v_cndmask_b32_e64 v66, 0, v108, s[6:7]
	v_cndmask_b32_e64 v68, 0, v108, s[4:5]
	v_cndmask_b32_e64 v70, 0, v108, s[16:17]
	global_load_dwordx4 v[40:43], v[40:41], off offset:3072
	v_lshl_add_u64 v[44:45], v[44:45], 0, v[58:59]
	v_lshl_add_u64 v[58:59], v[46:47], 0, v[60:61]
	v_lshl_add_u64 v[60:61], v[48:49], 0, v[62:63]
	v_lshl_add_u64 v[62:63], v[50:51], 0, v[64:65]
	v_lshl_add_u64 v[64:65], v[52:53], 0, v[66:67]
	v_lshl_add_u64 v[66:67], v[54:55], 0, v[68:69]
	v_lshl_add_u64 v[68:69], v[56:57], 0, v[70:71]
	global_load_dwordx4 v[24:27], v[48:49], off offset:3072
	global_load_dwordx4 v[20:23], v[50:51], off offset:3072
	s_nop 0
	global_load_dwordx4 v[44:47], v[44:45], off offset:3072
	s_nop 0
	global_load_dwordx4 v[48:51], v[58:59], off offset:3072
	global_load_dwordx4 v[52:55], v[60:61], off offset:3072
	s_nop 0
	global_load_dwordx4 v[56:59], v[62:63], off offset:3072
	s_nop 0
	global_load_dwordx4 v[60:63], v[64:65], off offset:3072
	s_nop 0
	global_load_dwordx4 v[64:67], v[66:67], off offset:3072
	s_nop 0
	global_load_dwordx4 v[68:71], v[68:69], off offset:3072
	v_or_b32_e32 v113, v113, v159
	v_add_u32_e32 v79, s36, v79
	s_waitcnt vmcnt(15)
	v_cvt_f32_f16_e32 v129, v36
	v_cvt_f32_f16_sdwa v131, v36 dst_sel:DWORD dst_unused:UNUSED_PAD src0_sel:WORD_1
	v_cvt_f32_f16_e32 v114, v37
	v_cvt_f32_f16_sdwa v115, v37 dst_sel:DWORD dst_unused:UNUSED_PAD src0_sel:WORD_1
	v_cvt_f32_f16_e32 v116, v38
	v_cvt_f32_f16_sdwa v117, v38 dst_sel:DWORD dst_unused:UNUSED_PAD src0_sel:WORD_1
	v_cvt_f32_f16_e32 v38, v39
	v_cvt_f32_f16_sdwa v39, v39 dst_sel:DWORD dst_unused:UNUSED_PAD src0_sel:WORD_1
	s_waitcnt vmcnt(14)
; __device__ __forceinline__ void phase2_main(const Params& p) {
;     ...
;             for (int q = 0; q < 8; ++q) {
;                 const int ta = (row0 + 2 * q + half) % TP;
;                 float o[8];
; #pragma unroll
;                 for (int e = 0; e < 8; ++e) {
;                     const float cf = (float)c[q][e], pf = ta > 0 ? (float)pv[q][e] : 0.f;
	v_cvt_f32_f16_e32 v37, v32
	v_cvt_f32_f16_sdwa v152, v32 dst_sel:DWORD dst_unused:UNUSED_PAD src0_sel:WORD_1
	v_cvt_f32_f16_e32 v118, v33
	s_waitcnt vmcnt(12)
	v_cvt_f32_f16_e32 v142, v18
	v_cvt_f32_f16_sdwa v143, v18 dst_sel:DWORD dst_unused:UNUSED_PAD src0_sel:WORD_1
	v_cvt_f32_f16_e32 v144, v19
	v_cvt_f32_f16_sdwa v145, v19 dst_sel:DWORD dst_unused:UNUSED_PAD src0_sel:WORD_1
	s_waitcnt vmcnt(11)
	v_cvt_f32_f16_e32 v148, v14
	v_cvt_f32_f16_sdwa v149, v14 dst_sel:DWORD dst_unused:UNUSED_PAD src0_sel:WORD_1
	v_cvt_f32_f16_e32 v150, v15
	v_cvt_f32_f16_sdwa v151, v15 dst_sel:DWORD dst_unused:UNUSED_PAD src0_sel:WORD_1
	s_waitcnt vmcnt(10)
	v_cvt_f32_f16_e32 v154, v9
	v_cvt_f32_f16_sdwa v155, v9 dst_sel:DWORD dst_unused:UNUSED_PAD src0_sel:WORD_1
	v_cvt_f32_f16_e32 v178, v10
	v_cvt_f32_f16_sdwa v179, v10 dst_sel:DWORD dst_unused:UNUSED_PAD src0_sel:WORD_1
	v_cvt_f32_f16_e32 v180, v11
	v_cvt_f32_f16_sdwa v181, v11 dst_sel:DWORD dst_unused:UNUSED_PAD src0_sel:WORD_1
	v_cvt_f32_f16_sdwa v119, v33 dst_sel:DWORD dst_unused:UNUSED_PAD src0_sel:WORD_1
	v_cvt_f32_f16_e32 v120, v34
	v_cvt_f32_f16_sdwa v121, v34 dst_sel:DWORD dst_unused:UNUSED_PAD src0_sel:WORD_1
	s_waitcnt vmcnt(9)
	v_cvt_f32_f16_e32 v9, v40
	v_cvt_f32_f16_sdwa v10, v40 dst_sel:DWORD dst_unused:UNUSED_PAD src0_sel:WORD_1
	v_cvt_f32_f16_sdwa v11, v41 dst_sel:DWORD dst_unused:UNUSED_PAD src0_sel:WORD_1
	v_cvt_f32_f16_e32 v14, v41
	v_cvt_f32_f16_sdwa v15, v42 dst_sel:DWORD dst_unused:UNUSED_PAD src0_sel:WORD_1
	v_cvt_f32_f16_e32 v18, v42
	v_cvt_f32_f16_sdwa v19, v43 dst_sel:DWORD dst_unused:UNUSED_PAD src0_sel:WORD_1
	v_cvt_f32_f16_e32 v40, v43
	s_waitcnt vmcnt(6)
	v_cvt_f32_f16_e32 v41, v44
	v_cvt_f32_f16_sdwa v42, v44 dst_sel:DWORD dst_unused:UNUSED_PAD src0_sel:WORD_1
	v_cvt_f32_f16_sdwa v43, v45 dst_sel:DWORD dst_unused:UNUSED_PAD src0_sel:WORD_1
	v_cvt_f32_f16_e32 v44, v45
	v_cvt_f32_f16_sdwa v45, v46 dst_sel:DWORD dst_unused:UNUSED_PAD src0_sel:WORD_1
	v_cvt_f32_f16_e32 v46, v46
	v_cvt_f32_f16_sdwa v182, v47 dst_sel:DWORD dst_unused:UNUSED_PAD src0_sel:WORD_1
	v_cvt_f32_f16_e32 v47, v47
	v_cvt_f32_f16_e32 v34, v35
	v_cvt_f32_f16_sdwa v35, v35 dst_sel:DWORD dst_unused:UNUSED_PAD src0_sel:WORD_1
	s_waitcnt vmcnt(5)
	v_cvt_f32_f16_e32 v183, v48
	v_cvt_f32_f16_sdwa v184, v48 dst_sel:DWORD dst_unused:UNUSED_PAD src0_sel:WORD_1
	v_cvt_f32_f16_sdwa v185, v49 dst_sel:DWORD dst_unused:UNUSED_PAD src0_sel:WORD_1
	v_cvt_f32_f16_e32 v186, v49
	v_cvt_f32_f16_sdwa v187, v50 dst_sel:DWORD dst_unused:UNUSED_PAD src0_sel:WORD_1
	v_cvt_f32_f16_e32 v188, v50
	v_cvt_f32_f16_sdwa v189, v51 dst_sel:DWORD dst_unused:UNUSED_PAD src0_sel:WORD_1
	v_cvt_f32_f16_e32 v190, v51
	s_waitcnt vmcnt(4)
	v_cvt_f32_f16_e32 v191, v52
	v_cvt_f32_f16_sdwa v192, v52 dst_sel:DWORD dst_unused:UNUSED_PAD src0_sel:WORD_1
	v_cvt_f32_f16_sdwa v193, v53 dst_sel:DWORD dst_unused:UNUSED_PAD src0_sel:WORD_1
	v_cvt_f32_f16_e32 v194, v53
	v_cvt_f32_f16_sdwa v195, v54 dst_sel:DWORD dst_unused:UNUSED_PAD src0_sel:WORD_1
	v_cvt_f32_f16_e32 v201, v54
	v_cvt_f32_f16_sdwa v202, v55 dst_sel:DWORD dst_unused:UNUSED_PAD src0_sel:WORD_1
	v_cvt_f32_f16_e32 v203, v55
	s_waitcnt vmcnt(3)
	v_cvt_f32_f16_e32 v204, v56
	v_cvt_f32_f16_sdwa v205, v56 dst_sel:DWORD dst_unused:UNUSED_PAD src0_sel:WORD_1
	v_cvt_f32_f16_sdwa v206, v57 dst_sel:DWORD dst_unused:UNUSED_PAD src0_sel:WORD_1
	v_cvt_f32_f16_e32 v207, v57
	v_cvt_f32_f16_sdwa v208, v58 dst_sel:DWORD dst_unused:UNUSED_PAD src0_sel:WORD_1
	v_cvt_f32_f16_e32 v209, v58
	v_cvt_f32_f16_sdwa v210, v59 dst_sel:DWORD dst_unused:UNUSED_PAD src0_sel:WORD_1
	v_cvt_f32_f16_e32 v211, v59
	s_waitcnt vmcnt(2)
	v_cvt_f32_f16_e32 v212, v60
	v_cvt_f32_f16_sdwa v213, v60 dst_sel:DWORD dst_unused:UNUSED_PAD src0_sel:WORD_1
	v_cvt_f32_f16_sdwa v214, v61 dst_sel:DWORD dst_unused:UNUSED_PAD src0_sel:WORD_1
	v_cvt_f32_f16_e32 v215, v61
	v_cvt_f32_f16_sdwa v216, v62 dst_sel:DWORD dst_unused:UNUSED_PAD src0_sel:WORD_1
	v_cvt_f32_f16_e32 v217, v62
	v_cvt_f32_f16_sdwa v218, v63 dst_sel:DWORD dst_unused:UNUSED_PAD src0_sel:WORD_1
	v_cvt_f32_f16_e32 v219, v63
	s_waitcnt vmcnt(1)
	v_cvt_f32_f16_e32 v220, v64
	v_cvt_f32_f16_sdwa v221, v64 dst_sel:DWORD dst_unused:UNUSED_PAD src0_sel:WORD_1
	v_cvt_f32_f16_sdwa v222, v65 dst_sel:DWORD dst_unused:UNUSED_PAD src0_sel:WORD_1
	v_cvt_f32_f16_e32 v223, v65
	v_cvt_f32_f16_sdwa v224, v66 dst_sel:DWORD dst_unused:UNUSED_PAD src0_sel:WORD_1
	v_cvt_f32_f16_e32 v225, v66
	v_cvt_f32_f16_sdwa v226, v67 dst_sel:DWORD dst_unused:UNUSED_PAD src0_sel:WORD_1
	v_cvt_f32_f16_e32 v227, v67
	s_waitcnt vmcnt(0)
; __device__ __forceinline__ void phase2_main(const Params& p) {
;     ...
;             for (int q = 0; q < 8; ++q) {
;                 const int ta = (row0 + 2 * q + half) % TP;
;                 float o[8];
; #pragma unroll
;                 for (int e = 0; e < 8; ++e) {
;                     const float cf = (float)c[q][e], pf = ta > 0 ? (float)pv[q][e] : 0.f;
;                     const float xs = cf + (e < 4 ? mA[e & 3] : mB[e & 3]) * (pf - cf);
	v_cvt_f32_f16_e32 v228, v68
	v_cvt_f32_f16_sdwa v229, v68 dst_sel:DWORD dst_unused:UNUSED_PAD src0_sel:WORD_1
	v_cvt_f32_f16_sdwa v230, v69 dst_sel:DWORD dst_unused:UNUSED_PAD src0_sel:WORD_1
	v_cvt_f32_f16_e32 v231, v69
	v_cvt_f32_f16_sdwa v232, v70 dst_sel:DWORD dst_unused:UNUSED_PAD src0_sel:WORD_1
	v_cvt_f32_f16_e32 v233, v70
	v_cvt_f32_f16_sdwa v234, v71 dst_sel:DWORD dst_unused:UNUSED_PAD src0_sel:WORD_1
	v_cvt_f32_f16_e32 v235, v71
	v_cvt_f32_f16_e32 v33, v28
	v_cvt_f32_f16_sdwa v177, v28 dst_sel:DWORD dst_unused:UNUSED_PAD src0_sel:WORD_1
	v_cvt_f32_f16_e32 v122, v29
	v_cvt_f32_f16_sdwa v123, v29 dst_sel:DWORD dst_unused:UNUSED_PAD src0_sel:WORD_1
	v_cvt_f32_f16_e32 v124, v30
	v_cvt_f32_f16_sdwa v125, v30 dst_sel:DWORD dst_unused:UNUSED_PAD src0_sel:WORD_1
	v_cvt_f32_f16_e32 v30, v31
	v_cvt_f32_f16_sdwa v31, v31 dst_sel:DWORD dst_unused:UNUSED_PAD src0_sel:WORD_1
	v_cvt_f32_f16_e32 v29, v24
	v_cvt_f32_f16_sdwa v196, v24 dst_sel:DWORD dst_unused:UNUSED_PAD src0_sel:WORD_1
	v_cvt_f32_f16_e32 v126, v25
	v_cvt_f32_f16_sdwa v127, v25 dst_sel:DWORD dst_unused:UNUSED_PAD src0_sel:WORD_1
	v_cvt_f32_f16_e32 v134, v26
	v_cvt_f32_f16_sdwa v135, v26 dst_sel:DWORD dst_unused:UNUSED_PAD src0_sel:WORD_1
	v_cvt_f32_f16_e32 v26, v27
	v_cvt_f32_f16_sdwa v27, v27 dst_sel:DWORD dst_unused:UNUSED_PAD src0_sel:WORD_1
	v_cvt_f32_f16_e32 v25, v20
	v_cvt_f32_f16_sdwa v197, v20 dst_sel:DWORD dst_unused:UNUSED_PAD src0_sel:WORD_1
	v_cvt_f32_f16_e32 v136, v21
	v_cvt_f32_f16_sdwa v137, v21 dst_sel:DWORD dst_unused:UNUSED_PAD src0_sel:WORD_1
	v_cvt_f32_f16_e32 v138, v22
	v_cvt_f32_f16_sdwa v139, v22 dst_sel:DWORD dst_unused:UNUSED_PAD src0_sel:WORD_1
	v_cvt_f32_f16_e32 v22, v23
	v_cvt_f32_f16_sdwa v23, v23 dst_sel:DWORD dst_unused:UNUSED_PAD src0_sel:WORD_1
	v_cvt_f32_f16_e32 v21, v16
	v_cvt_f32_f16_sdwa v198, v16 dst_sel:DWORD dst_unused:UNUSED_PAD src0_sel:WORD_1
	v_cvt_f32_f16_e32 v140, v17
	v_cvt_f32_f16_sdwa v141, v17 dst_sel:DWORD dst_unused:UNUSED_PAD src0_sel:WORD_1
	v_cvt_f32_f16_e32 v17, v12
	v_cvt_f32_f16_sdwa v199, v12 dst_sel:DWORD dst_unused:UNUSED_PAD src0_sel:WORD_1
	v_cvt_f32_f16_e32 v146, v13
	v_cvt_f32_f16_sdwa v147, v13 dst_sel:DWORD dst_unused:UNUSED_PAD src0_sel:WORD_1
	v_cvt_f32_f16_e32 v13, v8
	v_cvt_f32_f16_sdwa v200, v8 dst_sel:DWORD dst_unused:UNUSED_PAD src0_sel:WORD_1
	v_cndmask_b32_e64 v9, 0, v9, s[14:15]
	v_cndmask_b32_e64 v48, 0, v10, s[14:15]
	v_cndmask_b32_e64 v10, 0, v14, s[14:15]
	v_cndmask_b32_e64 v11, 0, v11, s[14:15]
	v_cndmask_b32_e64 v14, 0, v18, s[14:15]
	v_cndmask_b32_e64 v15, 0, v15, s[14:15]
	v_cndmask_b32_e64 v18, 0, v40, s[14:15]
	v_cndmask_b32_e64 v19, 0, v19, s[14:15]
	v_sub_f32_e32 v9, v9, v129
	v_sub_f32_e32 v129, v48, v131
	v_pk_add_f32 v[10:11], v[10:11], v[114:115] neg_lo:[0,1] neg_hi:[0,1]
	v_pk_add_f32 v[14:15], v[14:15], v[116:117] neg_lo:[0,1] neg_hi:[0,1]
	v_pk_add_f32 v[18:19], v[18:19], v[38:39] neg_lo:[0,1] neg_hi:[0,1]
	v_cndmask_b32_e64 v131, 0, v41, s[0:1]
	v_cndmask_b32_e64 v236, 0, v42, s[0:1]
	v_cndmask_b32_e64 v40, 0, v44, s[0:1]
	v_cndmask_b32_e64 v41, 0, v43, s[0:1]
	v_cndmask_b32_e64 v44, 0, v46, s[0:1]
	v_cndmask_b32_e64 v45, 0, v45, s[0:1]
	v_cndmask_b32_e64 v48, 0, v47, s[0:1]
	v_cndmask_b32_e64 v49, 0, v182, s[0:1]
	v_cndmask_b32_e64 v237, 0, v183, s[12:13]
	v_cndmask_b32_e64 v238, 0, v184, s[12:13]
	v_cndmask_b32_e64 v50, 0, v186, s[12:13]
	v_cndmask_b32_e64 v51, 0, v185, s[12:13]
	v_cndmask_b32_e64 v52, 0, v188, s[12:13]
	v_cndmask_b32_e64 v53, 0, v187, s[12:13]
	v_cndmask_b32_e64 v54, 0, v190, s[12:13]
	v_cndmask_b32_e64 v55, 0, v189, s[12:13]
	v_cndmask_b32_e64 v239, 0, v191, s[10:11]
	v_cndmask_b32_e64 v240, 0, v192, s[10:11]
	v_cndmask_b32_e64 v56, 0, v194, s[10:11]
	v_cndmask_b32_e64 v57, 0, v193, s[10:11]
	v_cndmask_b32_e64 v58, 0, v201, s[10:11]
	v_cndmask_b32_e64 v59, 0, v195, s[10:11]
	v_cndmask_b32_e64 v60, 0, v203, s[10:11]
	v_cndmask_b32_e64 v61, 0, v202, s[10:11]
	v_cndmask_b32_e64 v201, 0, v204, s[8:9]
	v_cndmask_b32_e64 v202, 0, v205, s[8:9]
	v_cndmask_b32_e64 v62, 0, v207, s[8:9]
	v_cndmask_b32_e64 v63, 0, v206, s[8:9]
	v_cndmask_b32_e64 v64, 0, v209, s[8:9]
	v_cndmask_b32_e64 v65, 0, v208, s[8:9]
	v_cndmask_b32_e64 v66, 0, v211, s[8:9]
	v_cndmask_b32_e64 v67, 0, v210, s[8:9]
	v_cndmask_b32_e64 v203, 0, v212, s[6:7]
	v_cndmask_b32_e64 v204, 0, v213, s[6:7]
	v_cndmask_b32_e64 v68, 0, v215, s[6:7]
	v_cndmask_b32_e64 v69, 0, v214, s[6:7]
	v_cndmask_b32_e64 v70, 0, v217, s[6:7]
	v_cndmask_b32_e64 v71, 0, v216, s[6:7]
	v_cndmask_b32_e64 v182, 0, v219, s[6:7]
	v_cndmask_b32_e64 v183, 0, v218, s[6:7]
	v_cndmask_b32_e64 v205, 0, v220, s[4:5]
	v_cndmask_b32_e64 v206, 0, v221, s[4:5]
	v_cndmask_b32_e64 v184, 0, v223, s[4:5]
	v_cndmask_b32_e64 v185, 0, v222, s[4:5]
	v_cndmask_b32_e64 v186, 0, v225, s[4:5]
	v_cndmask_b32_e64 v187, 0, v224, s[4:5]
	v_cndmask_b32_e64 v188, 0, v227, s[4:5]
	v_cndmask_b32_e64 v189, 0, v226, s[4:5]
	v_cndmask_b32_e64 v207, 0, v228, s[16:17]
	v_cndmask_b32_e64 v208, 0, v229, s[16:17]
	v_cndmask_b32_e64 v190, 0, v231, s[16:17]
	v_cndmask_b32_e64 v191, 0, v230, s[16:17]
	v_cndmask_b32_e64 v192, 0, v233, s[16:17]
	v_cndmask_b32_e64 v193, 0, v232, s[16:17]
	v_cndmask_b32_e64 v194, 0, v235, s[16:17]
	v_cndmask_b32_e64 v195, 0, v234, s[16:17]
	v_fma_mix_f32 v209, v4, v9, v36 op_sel_hi:[0,0,1]
	v_fma_mix_f32 v129, v5, v129, v36 op_sel:[0,0,1] op_sel_hi:[0,0,1]
	v_pk_fma_f32 v[46:47], v[6:7], v[10:11], v[114:115]
	v_pk_fma_f32 v[42:43], v[0:1], v[14:15], v[116:117]
	v_pk_fma_f32 v[38:39], v[2:3], v[18:19], v[38:39]
	v_sub_f32_e32 v9, v131, v37
	v_sub_f32_e32 v131, v236, v152
	v_pk_add_f32 v[10:11], v[40:41], v[118:119] neg_lo:[0,1] neg_hi:[0,1]
; __device__ __forceinline__ void phase2_main(const Params& p) {
;     ...
;                 for (int e = 0; e < 8; ++e) {
;                     const float cf = (float)c[q][e], pf = ta > 0 ? (float)pv[q][e] : 0.f;
;                     const float xs = cf + (e < 4 ? mA[e & 3] : mB[e & 3]) * (pf - cf);
;                     const float sg = __builtin_amdgcn_rcpf(1.0f + __expf(-sA * xs));
;                     o[e] = lin ? xs : sA * sg + sC;
	v_pk_add_f32 v[14:15], v[44:45], v[120:121] neg_lo:[0,1] neg_hi:[0,1]
	v_pk_add_f32 v[18:19], v[48:49], v[34:35] neg_lo:[0,1] neg_hi:[0,1]
	v_sub_f32_e32 v33, v237, v33
	v_sub_f32_e32 v40, v238, v177
	v_pk_add_f32 v[36:37], v[50:51], v[122:123] neg_lo:[0,1] neg_hi:[0,1]
	v_pk_add_f32 v[52:53], v[52:53], v[124:125] neg_lo:[0,1] neg_hi:[0,1]
	v_pk_add_f32 v[54:55], v[54:55], v[30:31] neg_lo:[0,1] neg_hi:[0,1]
	v_sub_f32_e32 v29, v239, v29
	v_sub_f32_e32 v152, v240, v196
	v_pk_add_f32 v[56:57], v[56:57], v[126:127] neg_lo:[0,1] neg_hi:[0,1]
	v_pk_add_f32 v[58:59], v[58:59], v[134:135] neg_lo:[0,1] neg_hi:[0,1]
	v_pk_add_f32 v[60:61], v[60:61], v[26:27] neg_lo:[0,1] neg_hi:[0,1]
	v_sub_f32_e32 v25, v201, v25
	v_sub_f32_e32 v177, v202, v197
	v_pk_add_f32 v[62:63], v[62:63], v[136:137] neg_lo:[0,1] neg_hi:[0,1]
	v_pk_add_f32 v[64:65], v[64:65], v[138:139] neg_lo:[0,1] neg_hi:[0,1]
	v_pk_add_f32 v[66:67], v[66:67], v[22:23] neg_lo:[0,1] neg_hi:[0,1]
	v_sub_f32_e32 v21, v203, v21
	v_sub_f32_e32 v196, v204, v198
	v_pk_add_f32 v[68:69], v[68:69], v[140:141] neg_lo:[0,1] neg_hi:[0,1]
	v_pk_add_f32 v[70:71], v[70:71], v[142:143] neg_lo:[0,1] neg_hi:[0,1]
	v_pk_add_f32 v[114:115], v[182:183], v[144:145] neg_lo:[0,1] neg_hi:[0,1]
	v_sub_f32_e32 v197, v205, v17
	v_sub_f32_e32 v198, v206, v199
	v_pk_add_f32 v[116:117], v[184:185], v[146:147] neg_lo:[0,1] neg_hi:[0,1]
	v_pk_add_f32 v[182:183], v[186:187], v[148:149] neg_lo:[0,1] neg_hi:[0,1]
	v_pk_add_f32 v[184:185], v[188:189], v[150:151] neg_lo:[0,1] neg_hi:[0,1]
	v_sub_f32_e32 v199, v207, v13
	v_sub_f32_e32 v200, v208, v200
	v_pk_add_f32 v[186:187], v[190:191], v[154:155] neg_lo:[0,1] neg_hi:[0,1]
	v_pk_add_f32 v[188:189], v[192:193], v[178:179] neg_lo:[0,1] neg_hi:[0,1]
	v_pk_add_f32 v[190:191], v[194:195], v[180:181] neg_lo:[0,1] neg_hi:[0,1]
	v_mul_f32_e32 v192, v209, v72
	v_mul_f32_e32 v193, v129, v72
	v_mul_f32_e32 v194, v46, v72
	v_mul_f32_e32 v195, v47, v72
	v_mul_f32_e32 v201, v42, v72
	v_mul_f32_e32 v202, v43, v72
	v_mul_f32_e32 v203, v38, v72
	v_mul_f32_e32 v204, v39, v72
	v_fma_mix_f32 v205, v4, v9, v32 op_sel_hi:[0,0,1]
	v_fma_mix_f32 v131, v5, v131, v32 op_sel:[0,0,1] op_sel_hi:[0,0,1]
	v_pk_fma_f32 v[50:51], v[6:7], v[10:11], v[118:119]
	v_pk_fma_f32 v[48:49], v[0:1], v[14:15], v[120:121]
	v_pk_fma_f32 v[44:45], v[2:3], v[18:19], v[34:35]
	v_fma_mix_f32 v206, v4, v33, v28 op_sel_hi:[0,0,1]
	v_fma_mix_f32 v207, v5, v40, v28 op_sel:[0,0,1] op_sel_hi:[0,0,1]
	v_pk_fma_f32 v[40:41], v[6:7], v[36:37], v[122:123]
	v_pk_fma_f32 v[36:37], v[0:1], v[52:53], v[124:125]
	v_pk_fma_f32 v[34:35], v[2:3], v[54:55], v[30:31]
	v_fma_mix_f32 v208, v4, v29, v24 op_sel_hi:[0,0,1]
	v_fma_mix_f32 v152, v5, v152, v24 op_sel:[0,0,1] op_sel_hi:[0,0,1]
	v_pk_fma_f32 v[32:33], v[6:7], v[56:57], v[126:127]
	v_pk_fma_f32 v[30:31], v[0:1], v[58:59], v[134:135]
	v_pk_fma_f32 v[28:29], v[2:3], v[60:61], v[26:27]
	v_fma_mix_f32 v210, v4, v25, v20 op_sel_hi:[0,0,1]
	v_fma_mix_f32 v177, v5, v177, v20 op_sel:[0,0,1] op_sel_hi:[0,0,1]
	v_pk_fma_f32 v[26:27], v[6:7], v[62:63], v[136:137]
	v_pk_fma_f32 v[24:25], v[0:1], v[64:65], v[138:139]
	v_pk_fma_f32 v[22:23], v[2:3], v[66:67], v[22:23]
	v_fma_mix_f32 v211, v4, v21, v16 op_sel_hi:[0,0,1]
	v_fma_mix_f32 v196, v5, v196, v16 op_sel:[0,0,1] op_sel_hi:[0,0,1]
	v_pk_fma_f32 v[20:21], v[6:7], v[68:69], v[140:141]
	v_pk_fma_f32 v[18:19], v[0:1], v[70:71], v[142:143]
	v_pk_fma_f32 v[16:17], v[2:3], v[114:115], v[144:145]
	v_fma_mix_f32 v144, v4, v197, v12 op_sel_hi:[0,0,1]
	v_fma_mix_f32 v145, v5, v198, v12 op_sel:[0,0,1] op_sel_hi:[0,0,1]
	v_pk_fma_f32 v[14:15], v[6:7], v[116:117], v[146:147]
	v_pk_fma_f32 v[12:13], v[0:1], v[182:183], v[148:149]
	v_pk_fma_f32 v[10:11], v[2:3], v[184:185], v[150:151]
	v_fma_mix_f32 v146, v4, v199, v8 op_sel_hi:[0,0,1]
	v_fma_mix_f32 v147, v5, v200, v8 op_sel:[0,0,1] op_sel_hi:[0,0,1]
	v_pk_fma_f32 v[6:7], v[6:7], v[186:187], v[154:155]
	v_pk_fma_f32 v[4:5], v[0:1], v[188:189], v[178:179]
	v_pk_fma_f32 v[0:1], v[2:3], v[190:191], v[180:181]
	v_mul_f32_e32 v2, 0xbfb8aa3b, v192
	v_mul_f32_e32 v3, 0xbfb8aa3b, v193
	v_mul_f32_e32 v8, 0xbfb8aa3b, v194
	v_mul_f32_e32 v9, 0xbfb8aa3b, v195
	v_mul_f32_e32 v52, 0xbfb8aa3b, v201
	v_mul_f32_e32 v53, 0xbfb8aa3b, v202
	v_mul_f32_e32 v54, 0xbfb8aa3b, v203
	v_mul_f32_e32 v55, 0xbfb8aa3b, v204
	v_mul_f32_e32 v56, v205, v72
	v_mul_f32_e32 v57, v131, v72
	v_mul_f32_e32 v58, v50, v72
	v_mul_f32_e32 v59, v51, v72
	v_mul_f32_e32 v60, v48, v72
	v_mul_f32_e32 v61, v49, v72
	v_mul_f32_e32 v62, v44, v72
	v_mul_f32_e32 v63, v45, v72
	v_mul_f32_e32 v64, v206, v72
	v_mul_f32_e32 v65, v207, v72
	v_mul_f32_e32 v66, v40, v72
	v_mul_f32_e32 v67, v41, v72
	v_mul_f32_e32 v68, v36, v72
	v_mul_f32_e32 v69, v37, v72
	v_mul_f32_e32 v70, v34, v72
	v_mul_f32_e32 v71, v35, v72
	v_mul_f32_e32 v114, v208, v72
	v_mul_f32_e32 v115, v152, v72
	v_mul_f32_e32 v116, v32, v72
	v_mul_f32_e32 v117, v33, v72
	v_mul_f32_e32 v118, v30, v72
	v_mul_f32_e32 v119, v31, v72
	v_mul_f32_e32 v120, v28, v72
	v_mul_f32_e32 v121, v29, v72
	v_mul_f32_e32 v122, v210, v72
	v_mul_f32_e32 v123, v177, v72
	v_mul_f32_e32 v124, v26, v72
	v_mul_f32_e32 v125, v27, v72
	v_mul_f32_e32 v126, v24, v72
	v_mul_f32_e32 v127, v25, v72
	v_mul_f32_e32 v134, v22, v72
	v_mul_f32_e32 v135, v23, v72
	v_mul_f32_e32 v136, v211, v72
	v_mul_f32_e32 v137, v196, v72
	v_mul_f32_e32 v138, v20, v72
	v_mul_f32_e32 v139, v21, v72
	v_mul_f32_e32 v140, v18, v72
	v_mul_f32_e32 v141, v19, v72
	v_mul_f32_e32 v142, v16, v72
	v_mul_f32_e32 v143, v17, v72
	v_mul_f32_e32 v148, v144, v72
	v_mul_f32_e32 v149, v145, v72
	v_mul_f32_e32 v150, v14, v72
	v_mul_f32_e32 v151, v15, v72
	v_mul_f32_e32 v154, v12, v72
; __device__ __forceinline__ void phase2_main(const Params& p) {
;     ...
;                     const float sg = __builtin_amdgcn_rcpf(1.0f + __expf(-sA * xs));
;                     o[e] = lin ? xs : sA * sg + sC;
	v_mul_f32_e32 v155, v13, v72
	v_mul_f32_e32 v178, v10, v72
	v_mul_f32_e32 v179, v11, v72
	v_mul_f32_e32 v180, v146, v72
	v_mul_f32_e32 v181, v147, v72
	v_mul_f32_e32 v182, v6, v72
	v_mul_f32_e32 v183, v7, v72
	v_mul_f32_e32 v184, v4, v72
	v_mul_f32_e32 v185, v5, v72
	v_mul_f32_e32 v186, v0, v72
	v_mul_f32_e32 v187, v1, v72
	v_exp_f32_e32 v2, v2
	v_exp_f32_e32 v3, v3
	v_exp_f32_e32 v8, v8
	v_exp_f32_e32 v9, v9
	v_exp_f32_e32 v52, v52
	v_exp_f32_e32 v53, v53
	v_exp_f32_e32 v54, v54
	v_exp_f32_e32 v55, v55
	v_mul_f32_e32 v56, 0xbfb8aa3b, v56
	v_mul_f32_e32 v57, 0xbfb8aa3b, v57
	v_mul_f32_e32 v58, 0xbfb8aa3b, v58
	v_mul_f32_e32 v59, 0xbfb8aa3b, v59
	v_mul_f32_e32 v60, 0xbfb8aa3b, v60
	v_mul_f32_e32 v61, 0xbfb8aa3b, v61
	v_mul_f32_e32 v62, 0xbfb8aa3b, v62
	v_mul_f32_e32 v63, 0xbfb8aa3b, v63
	v_mul_f32_e32 v64, 0xbfb8aa3b, v64
	v_mul_f32_e32 v65, 0xbfb8aa3b, v65
	v_mul_f32_e32 v66, 0xbfb8aa3b, v66
	v_mul_f32_e32 v67, 0xbfb8aa3b, v67
	v_mul_f32_e32 v68, 0xbfb8aa3b, v68
	v_mul_f32_e32 v69, 0xbfb8aa3b, v69
	v_mul_f32_e32 v70, 0xbfb8aa3b, v70
	v_mul_f32_e32 v71, 0xbfb8aa3b, v71
	v_mul_f32_e32 v114, 0xbfb8aa3b, v114
	v_mul_f32_e32 v115, 0xbfb8aa3b, v115
	v_mul_f32_e32 v116, 0xbfb8aa3b, v116
	v_mul_f32_e32 v117, 0xbfb8aa3b, v117
	v_mul_f32_e32 v118, 0xbfb8aa3b, v118
	v_mul_f32_e32 v119, 0xbfb8aa3b, v119
	v_mul_f32_e32 v120, 0xbfb8aa3b, v120
	v_mul_f32_e32 v121, 0xbfb8aa3b, v121
	v_mul_f32_e32 v122, 0xbfb8aa3b, v122
	v_mul_f32_e32 v123, 0xbfb8aa3b, v123
	v_mul_f32_e32 v124, 0xbfb8aa3b, v124
	v_mul_f32_e32 v125, 0xbfb8aa3b, v125
	v_mul_f32_e32 v126, 0xbfb8aa3b, v126
	v_mul_f32_e32 v127, 0xbfb8aa3b, v127
	v_mul_f32_e32 v134, 0xbfb8aa3b, v134
	v_mul_f32_e32 v135, 0xbfb8aa3b, v135
	v_mul_f32_e32 v136, 0xbfb8aa3b, v136
	v_mul_f32_e32 v137, 0xbfb8aa3b, v137
	v_mul_f32_e32 v138, 0xbfb8aa3b, v138
	v_mul_f32_e32 v139, 0xbfb8aa3b, v139
	v_mul_f32_e32 v140, 0xbfb8aa3b, v140
	v_mul_f32_e32 v141, 0xbfb8aa3b, v141
	v_mul_f32_e32 v142, 0xbfb8aa3b, v142
	v_mul_f32_e32 v143, 0xbfb8aa3b, v143
	v_mul_f32_e32 v148, 0xbfb8aa3b, v148
	v_mul_f32_e32 v149, 0xbfb8aa3b, v149
	v_mul_f32_e32 v150, 0xbfb8aa3b, v150
	v_mul_f32_e32 v151, 0xbfb8aa3b, v151
	v_mul_f32_e32 v154, 0xbfb8aa3b, v154
	v_mul_f32_e32 v155, 0xbfb8aa3b, v155
	v_mul_f32_e32 v178, 0xbfb8aa3b, v178
	v_mul_f32_e32 v179, 0xbfb8aa3b, v179
	v_mul_f32_e32 v180, 0xbfb8aa3b, v180
	v_mul_f32_e32 v181, 0xbfb8aa3b, v181
	v_mul_f32_e32 v182, 0xbfb8aa3b, v182
	v_mul_f32_e32 v183, 0xbfb8aa3b, v183
	v_mul_f32_e32 v184, 0xbfb8aa3b, v184
	v_mul_f32_e32 v185, 0xbfb8aa3b, v185
	v_mul_f32_e32 v186, 0xbfb8aa3b, v186
	v_mul_f32_e32 v187, 0xbfb8aa3b, v187
	v_exp_f32_e32 v56, v56
	v_exp_f32_e32 v57, v57
	v_exp_f32_e32 v58, v58
	v_exp_f32_e32 v59, v59
	v_exp_f32_e32 v60, v60
	v_exp_f32_e32 v61, v61
	v_exp_f32_e32 v62, v62
	v_exp_f32_e32 v63, v63
	v_exp_f32_e32 v64, v64
	v_exp_f32_e32 v65, v65
	v_exp_f32_e32 v66, v66
	v_exp_f32_e32 v67, v67
	v_exp_f32_e32 v68, v68
	v_exp_f32_e32 v69, v69
	v_exp_f32_e32 v70, v70
	v_exp_f32_e32 v71, v71
	v_exp_f32_e32 v114, v114
	v_exp_f32_e32 v115, v115
	v_exp_f32_e32 v116, v116
	v_exp_f32_e32 v117, v117
	v_exp_f32_e32 v118, v118
	v_exp_f32_e32 v119, v119
	v_exp_f32_e32 v120, v120
	v_exp_f32_e32 v121, v121
	v_exp_f32_e32 v122, v122
	v_exp_f32_e32 v123, v123
	v_exp_f32_e32 v124, v124
	v_exp_f32_e32 v125, v125
	v_exp_f32_e32 v126, v126
	v_exp_f32_e32 v127, v127
	v_exp_f32_e32 v134, v134
	v_exp_f32_e32 v135, v135
	v_exp_f32_e32 v136, v136
	v_exp_f32_e32 v137, v137
	v_exp_f32_e32 v138, v138
	v_exp_f32_e32 v139, v139
	v_exp_f32_e32 v140, v140
	v_exp_f32_e32 v141, v141
	v_exp_f32_e32 v142, v142
	v_exp_f32_e32 v143, v143
	v_exp_f32_e32 v148, v148
	v_exp_f32_e32 v149, v149
	v_exp_f32_e32 v150, v150
	v_exp_f32_e32 v151, v151
	v_exp_f32_e32 v154, v154
	v_exp_f32_e32 v155, v155
	v_exp_f32_e32 v178, v178
	v_exp_f32_e32 v179, v179
	v_exp_f32_e32 v180, v180
	v_exp_f32_e32 v181, v181
	v_exp_f32_e32 v182, v182
	v_exp_f32_e32 v183, v183
	v_exp_f32_e32 v184, v184
	v_exp_f32_e32 v185, v185
	v_exp_f32_e32 v186, v186
	v_exp_f32_e32 v187, v187
	v_add_f32_e32 v2, 1.0, v2
	v_add_f32_e32 v3, 1.0, v3
	v_add_f32_e32 v8, 1.0, v8
	v_add_f32_e32 v9, 1.0, v9
	v_add_f32_e32 v52, 1.0, v52
	v_add_f32_e32 v53, 1.0, v53
	v_add_f32_e32 v54, 1.0, v54
	v_add_f32_e32 v55, 1.0, v55
	v_rcp_f32_e32 v188, v2
	v_rcp_f32_e32 v189, v3
	v_rcp_f32_e32 v2, v8
	v_rcp_f32_e32 v3, v9
	v_rcp_f32_e32 v8, v52
	v_rcp_f32_e32 v9, v53
	v_rcp_f32_e32 v52, v54
	v_rcp_f32_e32 v53, v55
	v_add_f32_e32 v54, 1.0, v56
	v_add_f32_e32 v55, 1.0, v57
	v_add_f32_e32 v56, 1.0, v58
	v_add_f32_e32 v57, 1.0, v59
	v_add_f32_e32 v58, 1.0, v60
	v_add_f32_e32 v59, 1.0, v61
	v_add_f32_e32 v60, 1.0, v62
	v_add_f32_e32 v61, 1.0, v63
	v_add_f32_e32 v62, 1.0, v64
	v_add_f32_e32 v63, 1.0, v65
	v_add_f32_e32 v64, 1.0, v66
	v_add_f32_e32 v65, 1.0, v67
	v_add_f32_e32 v66, 1.0, v68
	v_add_f32_e32 v67, 1.0, v69
	v_add_f32_e32 v68, 1.0, v70
	v_add_f32_e32 v69, 1.0, v71
	v_add_f32_e32 v70, 1.0, v114
	v_add_f32_e32 v71, 1.0, v115
	v_add_f32_e32 v114, 1.0, v116
	v_add_f32_e32 v115, 1.0, v117
	v_add_f32_e32 v116, 1.0, v118
	v_add_f32_e32 v117, 1.0, v119
	v_add_f32_e32 v118, 1.0, v120
	v_add_f32_e32 v119, 1.0, v121
	v_add_f32_e32 v120, 1.0, v122
	v_add_f32_e32 v121, 1.0, v123
	v_add_f32_e32 v122, 1.0, v124
	v_add_f32_e32 v123, 1.0, v125
	v_add_f32_e32 v124, 1.0, v126
	v_add_f32_e32 v125, 1.0, v127
	v_add_f32_e32 v126, 1.0, v134
	v_add_f32_e32 v127, 1.0, v135
	v_add_f32_e32 v134, 1.0, v136
	v_add_f32_e32 v135, 1.0, v137
	v_add_f32_e32 v136, 1.0, v138
	v_add_f32_e32 v137, 1.0, v139
	v_add_f32_e32 v138, 1.0, v140
	v_add_f32_e32 v139, 1.0, v141
	v_add_f32_e32 v140, 1.0, v142
	v_add_f32_e32 v141, 1.0, v143
; __device__ __forceinline__ unsigned pk_bf16(float lo, float hi) { const f32x2 v = {lo, hi}; return __builtin_bit_cast(unsigned, __builtin_convertvector(v, b16x2)); }
; __device__ __forceinline__ void phase2_main(const Params& p) {
;     ...
;             for (int q = 0; q < 8; ++q) {
;                 const int ta = (row0 + 2 * q + half) % TP;
;                 float o[8];
; #pragma unroll
;                 for (int e = 0; e < 8; ++e) {
;                     const float cf = (float)c[q][e], pf = ta > 0 ? (float)pv[q][e] : 0.f;
;                     const float xs = cf + (e < 4 ? mA[e & 3] : mB[e & 3]) * (pf - cf);
;                     const float sg = __builtin_amdgcn_rcpf(1.0f + __expf(-sA * xs));
;                     o[e] = lin ? xs : sA * sg + sC;
;                 }
;                 u32x4 w; w.x = pk_bf16(o[0], o[1]); w.y = pk_bf16(o[2], o[3]); w.z = pk_bf16(o[4], o[5]); w.w = pk_bf16(o[6], o[7]);
;                 *(u32x4*)(Al + (2 * q + half) * ALD + pc) = w;
	v_add_f32_e32 v142, 1.0, v148
	v_add_f32_e32 v143, 1.0, v149
	v_add_f32_e32 v148, 1.0, v150
	v_add_f32_e32 v149, 1.0, v151
	v_add_f32_e32 v150, 1.0, v154
	v_add_f32_e32 v151, 1.0, v155
	v_add_f32_e32 v154, 1.0, v178
	v_add_f32_e32 v155, 1.0, v179
	v_add_f32_e32 v178, 1.0, v180
	v_add_f32_e32 v179, 1.0, v181
	v_add_f32_e32 v180, 1.0, v182
	v_add_f32_e32 v181, 1.0, v183
	v_add_f32_e32 v182, 1.0, v184
	v_add_f32_e32 v183, 1.0, v185
	v_add_f32_e32 v184, 1.0, v186
	v_add_f32_e32 v185, 1.0, v187
	v_rcp_f32_e32 v186, v54
	v_rcp_f32_e32 v187, v55
	v_rcp_f32_e32 v54, v56
	v_rcp_f32_e32 v55, v57
	v_rcp_f32_e32 v56, v58
	v_rcp_f32_e32 v57, v59
	v_rcp_f32_e32 v58, v60
	v_rcp_f32_e32 v59, v61
	v_rcp_f32_e32 v190, v62
	v_rcp_f32_e32 v191, v63
	v_rcp_f32_e32 v60, v64
	v_rcp_f32_e32 v61, v65
	v_rcp_f32_e32 v62, v66
	v_rcp_f32_e32 v63, v67
	v_rcp_f32_e32 v64, v68
	v_rcp_f32_e32 v65, v69
	v_rcp_f32_e32 v192, v70
	v_rcp_f32_e32 v193, v71
	v_rcp_f32_e32 v66, v114
	v_rcp_f32_e32 v67, v115
	v_rcp_f32_e32 v68, v116
	v_rcp_f32_e32 v69, v117
	v_rcp_f32_e32 v70, v118
	v_rcp_f32_e32 v71, v119
	v_rcp_f32_e32 v194, v120
	v_rcp_f32_e32 v195, v121
	v_rcp_f32_e32 v114, v122
	v_rcp_f32_e32 v115, v123
	v_rcp_f32_e32 v116, v124
	v_rcp_f32_e32 v117, v125
	v_rcp_f32_e32 v118, v126
	v_rcp_f32_e32 v119, v127
	v_rcp_f32_e32 v197, v134
	v_rcp_f32_e32 v198, v135
	v_rcp_f32_e32 v120, v136
	v_rcp_f32_e32 v121, v137
	v_rcp_f32_e32 v122, v138
	v_rcp_f32_e32 v123, v139
	v_rcp_f32_e32 v124, v140
	v_rcp_f32_e32 v125, v141
	v_rcp_f32_e32 v199, v142
	v_rcp_f32_e32 v200, v143
	v_rcp_f32_e32 v126, v148
	v_rcp_f32_e32 v127, v149
	v_rcp_f32_e32 v134, v150
	v_rcp_f32_e32 v135, v151
	v_rcp_f32_e32 v136, v154
	v_rcp_f32_e32 v137, v155
	v_rcp_f32_e32 v148, v178
	v_rcp_f32_e32 v149, v179
	v_rcp_f32_e32 v138, v180
	v_rcp_f32_e32 v139, v181
	v_rcp_f32_e32 v140, v182
	v_rcp_f32_e32 v141, v183
	v_rcp_f32_e32 v142, v184
	v_rcp_f32_e32 v143, v185
	v_fma_f32 v150, v72, v188, v74
	v_fma_f32 v151, v72, v189, v74
	v_pk_fma_f32 v[2:3], v[72:73], v[2:3], v[74:75]
	v_pk_fma_f32 v[8:9], v[72:73], v[8:9], v[74:75]
	v_pk_fma_f32 v[52:53], v[72:73], v[52:53], v[74:75]
	v_cndmask_b32_e32 v150, v150, v209, vcc
	v_cndmask_b32_e32 v129, v151, v129, vcc
	v_cndmask_b32_e32 v151, v3, v47, vcc
	v_cndmask_b32_e32 v154, v2, v46, vcc
	v_cndmask_b32_e32 v155, v9, v43, vcc
	v_cndmask_b32_e32 v178, v8, v42, vcc
	v_cndmask_b32_e32 v179, v53, v39, vcc
	v_cndmask_b32_e32 v180, v52, v38, vcc
	v_fma_f32 v181, v72, v186, v74
	v_fma_f32 v182, v72, v187, v74
	v_pk_fma_f32 v[2:3], v[72:73], v[54:55], v[74:75]
	v_pk_fma_f32 v[8:9], v[72:73], v[56:57], v[74:75]
	v_pk_fma_f32 v[38:39], v[72:73], v[58:59], v[74:75]
	v_fma_f32 v183, v72, v190, v74
	v_fma_f32 v184, v72, v191, v74
	v_pk_fma_f32 v[42:43], v[72:73], v[60:61], v[74:75]
	v_pk_fma_f32 v[46:47], v[72:73], v[62:63], v[74:75]
	v_pk_fma_f32 v[56:57], v[72:73], v[64:65], v[74:75]
	v_fma_f32 v185, v72, v192, v74
	v_fma_f32 v186, v72, v193, v74
	v_pk_fma_f32 v[58:59], v[72:73], v[66:67], v[74:75]
	v_pk_fma_f32 v[60:61], v[72:73], v[68:69], v[74:75]
	v_pk_fma_f32 v[62:63], v[72:73], v[70:71], v[74:75]
	v_fma_f32 v187, v72, v194, v74
	v_fma_f32 v188, v72, v195, v74
	v_pk_fma_f32 v[64:65], v[72:73], v[114:115], v[74:75]
	v_pk_fma_f32 v[66:67], v[72:73], v[116:117], v[74:75]
	v_pk_fma_f32 v[68:69], v[72:73], v[118:119], v[74:75]
	v_fma_f32 v189, v72, v197, v74
	v_fma_f32 v190, v72, v198, v74
	v_pk_fma_f32 v[70:71], v[72:73], v[120:121], v[74:75]
	v_pk_fma_f32 v[114:115], v[72:73], v[122:123], v[74:75]
	v_pk_fma_f32 v[116:117], v[72:73], v[124:125], v[74:75]
	v_fma_f32 v191, v72, v199, v74
	v_fma_f32 v192, v72, v200, v74
	v_pk_fma_f32 v[118:119], v[72:73], v[126:127], v[74:75]
	v_pk_fma_f32 v[120:121], v[72:73], v[134:135], v[74:75]
	v_pk_fma_f32 v[122:123], v[72:73], v[136:137], v[74:75]
	v_fma_f32 v136, v72, v148, v74
	v_fma_f32 v137, v72, v149, v74
	v_pk_fma_f32 v[124:125], v[72:73], v[138:139], v[74:75]
	v_pk_fma_f32 v[126:127], v[72:73], v[140:141], v[74:75]
	v_pk_fma_f32 v[134:135], v[72:73], v[142:143], v[74:75]
	v_cvt_pk_bf16_f32 v52, v150, v129
	v_cndmask_b32_e32 v129, v181, v205, vcc
	v_cndmask_b32_e32 v131, v182, v131, vcc
	v_cndmask_b32_e32 v3, v3, v51, vcc
	v_cndmask_b32_e32 v2, v2, v50, vcc
	v_cndmask_b32_e32 v9, v9, v49, vcc
	v_cndmask_b32_e32 v8, v8, v48, vcc
	v_cndmask_b32_e32 v39, v39, v45, vcc
	v_cndmask_b32_e32 v38, v38, v44, vcc
	v_cvt_pk_bf16_f32 v53, v154, v151
	v_cvt_pk_bf16_f32 v54, v178, v155
	v_cvt_pk_bf16_f32 v55, v180, v179
	v_cndmask_b32_e32 v44, v183, v206, vcc
	v_cndmask_b32_e32 v45, v184, v207, vcc
	v_cndmask_b32_e32 v41, v43, v41, vcc
	v_cndmask_b32_e32 v40, v42, v40, vcc
	v_cndmask_b32_e32 v37, v47, v37, vcc
	v_cndmask_b32_e32 v36, v46, v36, vcc
	v_cndmask_b32_e32 v35, v57, v35, vcc
	v_cndmask_b32_e32 v34, v56, v34, vcc
	v_cndmask_b32_e32 v42, v185, v208, vcc
	v_cndmask_b32_e32 v43, v186, v152, vcc
	v_cndmask_b32_e32 v33, v59, v33, vcc
	v_cndmask_b32_e32 v32, v58, v32, vcc
	v_cndmask_b32_e32 v31, v61, v31, vcc
	v_cndmask_b32_e32 v30, v60, v30, vcc
	v_cndmask_b32_e32 v29, v63, v29, vcc
	v_cndmask_b32_e32 v28, v62, v28, vcc
	v_cndmask_b32_e32 v46, v187, v210, vcc
	v_cndmask_b32_e32 v47, v188, v177, vcc
	v_cndmask_b32_e32 v27, v65, v27, vcc
	v_cndmask_b32_e32 v26, v64, v26, vcc
	v_cndmask_b32_e32 v25, v67, v25, vcc
	v_cndmask_b32_e32 v24, v66, v24, vcc
	v_cndmask_b32_e32 v23, v69, v23, vcc
	v_cndmask_b32_e32 v22, v68, v22, vcc
	v_cndmask_b32_e32 v48, v189, v211, vcc
	v_cndmask_b32_e32 v49, v190, v196, vcc
	v_cndmask_b32_e32 v21, v71, v21, vcc
	v_cndmask_b32_e32 v20, v70, v20, vcc
	v_cndmask_b32_e32 v19, v115, v19, vcc
	v_cndmask_b32_e32 v18, v114, v18, vcc
; __device__ __forceinline__ unsigned pk_bf16(float lo, float hi) { const f32x2 v = {lo, hi}; return __builtin_bit_cast(unsigned, __builtin_convertvector(v, b16x2)); }
;     __device__ __forceinline__ void row(int r, int col32, int fq, const f32x4& a00, const f32x4& a01, const f32x4& a10, const f32x4& a11) const { half(r, col32, fq, a00, a01); half(r, col32 + HALF, fq, a10, a11); }
;     __device__ __forceinline__ void row(int r, int col32, int fq, const f32x4& a00, const f32x4& a01, const f32x4& a10, const f32x4& a11) const { half(r, col32, fq, a00, a01); half(r, col32 + HALF, fq, a10, a11); }
;     __device__ __forceinline__ void row(int r, int col32, int fq, const f32x4& a00, const f32x4& a01, const f32x4& a10, const f32x4& a11) const { half(r, col32, fq, a00, a01); half(r, col32 + HALF, fq, a10, a11); }
; __device__ __forceinline__ void phase2_main(const Params& p) {
;     ...
;                 u32x4 w; w.x = pk_bf16(o[0], o[1]); w.y = pk_bf16(o[2], o[3]); w.z = pk_bf16(o[4], o[5]); w.w = pk_bf16(o[6], o[7]);
;                 *(u32x4*)(Al + (2 * q + half) * ALD + pc) = w;
;             }
;         }
;         asm volatile("s_waitcnt lgkmcnt(0)" ::: "memory");
;         __builtin_amdgcn_wave_barrier();
;         f32x4 acc[4];
;         auto lora = [&](auto kbeg_c, auto ksteps_c) {
;             constexpr int kbeg = decltype(kbeg_c)::value, ksteps = decltype(ksteps_c)::value;
; #pragma unroll
;             for (int n = 0; n < 4; ++n) acc[n] = (f32x4){0.f, 0.f, 0.f, 0.f};
; #pragma unroll
;             for (int ks = 0; ks < ksteps; ++ks) {
;                 const bf16x8 af = *(const bf16x8*)(Al + fr * ALD + kbeg + ks * 32 + fq * 8);
; #pragma unroll
;                 for (int n = 0; n < 4; ++n) {
;                     const bf16x8 wf = *(const bf16x8*)(WLs + (n * 16 + fr) * ALD + kbeg + ks * 32 + fq * 8);
;                     acc[n] = __builtin_amdgcn_mfma_f32_16x16x32_bf16(wf, af, acc[n], 0, 0, 0);
;                 }
;             }
;         };
;         const int row = row0 + fr, b = row / TP, t = row - b * TP;
;         const size_t base = ((size_t)(b * NH + h) * TP + t) * 448;
;         const _Float16* ur = urw + (size_t)row * RWS;
;         const size_t pb = base + fq * 16;
;         lora(std::integral_constant<int, 0>{}, std::integral_constant<int, 2>{});
	v_cndmask_b32_e32 v50, v117, v17, vcc
	v_cndmask_b32_e32 v51, v116, v16, vcc
	v_cndmask_b32_e32 v56, v191, v144, vcc
	v_cndmask_b32_e32 v57, v192, v145, vcc
	v_cndmask_b32_e32 v58, v119, v15, vcc
	v_cndmask_b32_e32 v59, v118, v14, vcc
	v_cndmask_b32_e32 v60, v121, v13, vcc
	v_cndmask_b32_e32 v61, v120, v12, vcc
	v_cndmask_b32_e32 v62, v123, v11, vcc
	v_cndmask_b32_e32 v63, v122, v10, vcc
	v_cndmask_b32_e32 v64, v136, v146, vcc
	v_cndmask_b32_e32 v65, v137, v147, vcc
	v_cndmask_b32_e32 v66, v125, v7, vcc
	v_cndmask_b32_e32 v67, v124, v6, vcc
	v_cndmask_b32_e32 v68, v127, v5, vcc
	v_cndmask_b32_e32 v69, v126, v4, vcc
	v_cndmask_b32_e32 v70, v135, v1, vcc
	v_cndmask_b32_e32 v71, v134, v0, vcc
	v_cvt_pk_bf16_f32 v0, v129, v131
	v_cvt_pk_bf16_f32 v1, v2, v3
	v_cvt_pk_bf16_f32 v2, v8, v9
	v_cvt_pk_bf16_f32 v3, v38, v39
	ds_write_b128 v107, v[52:55] offset:34816
	v_cvt_pk_bf16_f32 v4, v44, v45
	v_cvt_pk_bf16_f32 v5, v40, v41
	v_cvt_pk_bf16_f32 v6, v36, v37
	v_cvt_pk_bf16_f32 v7, v34, v35
	v_cvt_pk_bf16_f32 v8, v42, v43
	v_cvt_pk_bf16_f32 v9, v32, v33
	v_cvt_pk_bf16_f32 v10, v30, v31
	v_cvt_pk_bf16_f32 v11, v28, v29
	v_cvt_pk_bf16_f32 v12, v46, v47
	v_cvt_pk_bf16_f32 v13, v26, v27
	v_cvt_pk_bf16_f32 v14, v24, v25
	v_cvt_pk_bf16_f32 v15, v22, v23
	v_cvt_pk_bf16_f32 v16, v48, v49
	v_cvt_pk_bf16_f32 v17, v20, v21
	v_cvt_pk_bf16_f32 v18, v18, v19
	v_cvt_pk_bf16_f32 v19, v51, v50
	v_cvt_pk_bf16_f32 v20, v56, v57
	v_cvt_pk_bf16_f32 v21, v59, v58
	v_cvt_pk_bf16_f32 v22, v61, v60
	v_cvt_pk_bf16_f32 v23, v63, v62
	v_cvt_pk_bf16_f32 v24, v64, v65
	v_cvt_pk_bf16_f32 v25, v67, v66
	v_cvt_pk_bf16_f32 v26, v69, v68
	v_cvt_pk_bf16_f32 v27, v71, v70
	ds_write_b128 v107, v[0:3] offset:35872
	ds_write_b128 v107, v[4:7] offset:36928
	ds_write_b128 v107, v[8:11] offset:37984
	ds_write_b128 v107, v[12:15] offset:39040
	ds_write_b128 v107, v[16:19] offset:40096
	ds_write_b128 v107, v[20:23] offset:41152
	ds_write_b128 v107, v[24:27] offset:42208
	s_waitcnt lgkmcnt(0)
	ds_read_b128 v[4:7], v106
	ds_read_b128 v[8:11], v106 offset:8448
	ds_read_b128 v[12:15], v105 offset:34816
	ds_read_b128 v[0:3], v105 offset:34880
	ds_read_b128 v[56:59], v106 offset:64
	s_waitcnt lgkmcnt(2)
	v_mfma_f32_16x16x32_bf16 v[60:63], v[4:7], v[12:15], 0
	ds_read_b128 v[4:7], v106 offset:16896
	ds_read_b128 v[40:43], v106 offset:8512
	ds_read_b128 v[20:23], v106 offset:25344
	ds_read_b128 v[16:19], v106 offset:16960
	v_mul_hi_i32 v129, v113, s41
	v_mfma_f32_16x16x32_bf16 v[52:55], v[8:11], v[12:15], 0
	ds_read_b128 v[28:31], v106 offset:128
	ds_read_b128 v[8:11], v106 offset:25408
	ds_read_b128 v[48:51], v106 offset:8576
	v_mad_i64_i32 v[126:127], s[0:1], v113, s42, v[80:81]
	s_waitcnt lgkmcnt(6)
	v_mfma_f32_16x16x32_bf16 v[32:35], v[4:7], v[12:15], 0
	ds_read_b128 v[64:67], v105 offset:34944
	ds_read_b128 v[4:7], v105 offset:35008
	ds_read_b128 v[24:27], v106 offset:192
	s_waitcnt lgkmcnt(7)
	v_mfma_f32_16x16x32_bf16 v[36:39], v[20:23], v[12:15], 0
	s_waitcnt lgkmcnt(2)
	v_mfma_f32_16x16x32_bf16 v[44:47], v[28:31], v[64:67], 0
	ds_read_b128 v[20:23], v106 offset:17024
	ds_read_b128 v[28:31], v106 offset:8640
	ds_read_b128 v[68:71], v106 offset:25472
	ds_read_b128 v[12:15], v106 offset:17088
	ds_read_b128 v[114:117], v106 offset:256
	ds_read_b128 v[118:121], v106 offset:25536
	v_mfma_f32_16x16x32_bf16 v[48:51], v[48:51], v[64:67], 0
	v_mfma_f32_16x16x32_bf16 v[56:59], v[56:59], v[0:3], v[60:63]
	s_nop 2
	v_lshrrev_b32_e32 v60, 31, v129
	v_ashrrev_i32_e32 v61, 12, v129
	v_mfma_f32_16x16x32_bf16 v[40:43], v[40:43], v[0:3], v[52:55]
	s_nop 2
	v_add_u32_e32 v52, v61, v60
	s_waitcnt lgkmcnt(5)
	v_mfma_f32_16x16x32_bf16 v[20:23], v[20:23], v[64:67], 0
	v_mad_i32_i24 v60, v52, s43, v113
	v_lshl_or_b32 v61, v52, 3, s60
	v_cmp_lt_i32_e64 s[0:1], 0, v60
	s_waitcnt lgkmcnt(3)
	v_mfma_f32_16x16x32_bf16 v[64:67], v[68:71], v[64:67], 0
	ds_read_b128 v[68:71], v105 offset:35072
	ds_read_b128 v[122:125], v105 offset:35136
	ds_read_b128 v[134:137], v106 offset:320
	ds_read_b128 v[138:141], v106 offset:8704
	ds_read_b128 v[142:145], v106 offset:8768
	ds_read_b128 v[146:149], v106 offset:17152
	ds_read_b128 v[178:181], v106 offset:17216
	ds_read_b128 v[182:185], v106 offset:25600
	ds_read_b128 v[186:189], v106 offset:25664
	v_mfma_f32_16x16x32_bf16 v[52:55], v[16:19], v[0:3], v[32:35]
	v_mul_hi_i32_i24_e32 v17, 0x2080, v61
	v_mul_i32_i24_e32 v16, 0x2080, v61
	v_ashrrev_i32_e32 v61, 31, v60
	v_mfma_f32_16x16x32_bf16 v[36:39], v[8:11], v[0:3], v[36:39]
	v_lshl_add_u64 v[2:3], v[16:17], 0, v[60:61]
	v_cndmask_b32_e64 v1, 0, -1, s[0:1]
	v_cndmask_b32_e64 v0, 0, v108, s[0:1]
	v_mfma_f32_16x16x32_bf16 v[16:19], v[28:31], v[4:7], v[48:51]
	v_mad_u64_u32 v[8:9], s[4:5], v2, s52, 0
	v_lshl_add_u64 v[150:151], v[126:127], 0, v[0:1]
	s_nop 0
	ds_read_b128 v[48:51], v106 offset:384
	s_waitcnt lgkmcnt(9)
	v_mfma_f32_16x16x32_bf16 v[114:117], v[114:117], v[68:71], 0
	v_mov_b32_e32 v0, v9
	v_or_b32_e32 v10, v8, v78
	s_waitcnt lgkmcnt(6)
	v_mfma_f32_16x16x32_bf16 v[138:141], v[138:141], v[68:71], 0
	s_waitcnt lgkmcnt(4)
	v_mfma_f32_16x16x32_bf16 v[146:149], v[146:149], v[68:71], 0
	s_waitcnt lgkmcnt(2)
	v_mfma_f32_16x16x32_bf16 v[68:71], v[182:185], v[68:71], 0
	v_mfma_f32_16x16x32_bf16 v[44:47], v[24:27], v[4:7], v[44:47]
	v_mfma_f32_16x16x32_bf16 v[12:15], v[12:15], v[4:7], v[20:23]
	s_nop 2
	v_mad_u64_u32 v[20:21], s[4:5], v3, s52, v[0:1]
	v_mfma_f32_16x16x32_bf16 v[0:3], v[118:121], v[4:7], v[64:67]
	v_mov_b32_e32 v9, v20
	v_mov_b32_e32 v11, v20
	v_lshlrev_b64 v[20:21], 1, v[10:11]
	v_mfma_f32_16x16x32_bf16 v[4:7], v[134:137], v[122:125], v[114:117]
	v_lshl_add_u64 v[32:33], v[8:9], 1, v[102:103]
	v_lshl_add_u64 v[154:155], s[22:23], 0, v[20:21]
	v_lshl_add_u64 v[34:35], s[20:21], 0, v[20:21]
	s_waitcnt lgkmcnt(1)
; __device__ __forceinline__ unsigned pk_bf16(float lo, float hi) { const f32x2 v = {lo, hi}; return __builtin_bit_cast(unsigned, __builtin_convertvector(v, b16x2)); }
; __device__ __forceinline__ float sigmoidf_(float x) { return __builtin_amdgcn_rcpf(1.0f + __expf(-x)); }
; __device__ __forceinline__ void phase2_main(const Params& p) {
;     ...
;         lora(std::integral_constant<int, 0>{}, std::integral_constant<int, 2>{});
;         {
;             h16x8 wo[2];
; #pragma unroll
;             for (int n = 0; n < 4; ++n) {
;                 const f32x4 db = *(const f32x4*)(p.in[7] + h * 64 + n * 16 + fq * 4);
; #pragma unroll
;                 for (int j = 0; j < 4; ++j) {
;                     const float e = sigmoidf_(db[j] + acc[n][j]) * 0.60653065971f;
;                     wo[n >> 1][(n & 1) * 4 + j] = (_Float16)(1.0f - __expf(-e));
;                 }
;             }
;             *(h16x8*)(SI + SI_W * 64 + pb) = wo[0]; *(h16x8*)(SI + SI_W * 64 + pb + 8) = wo[1];
;     ...
;         lora(std::integral_constant<int, 128>{}, std::integral_constant<int, 4>{});
;         {
;             u32x4 g0, g1;
;             g0.x = pk_bf16(acc[0][0], acc[0][1]); g0.y = pk_bf16(acc[0][2], acc[0][3]); g0.z = pk_bf16(acc[1][0], acc[1][1]); g0.w = pk_bf16(acc[1][2], acc[1][3]);
;             g1.x = pk_bf16(acc[2][0], acc[2][1]); g1.y = pk_bf16(acc[2][2], acc[2][3]); g1.z = pk_bf16(acc[3][0], acc[3][1]); g1.w = pk_bf16(acc[3][2], acc[3][3]);
;             *(u32x4*)((bf16_t*)SI + 6 * 64 + pb) = g0; *(u32x4*)((bf16_t*)SI + 6 * 64 + pb + 8) = g1;
	v_mfma_f32_16x16x32_bf16 v[60:63], v[186:189], v[122:125], v[68:71]
	ds_read_b128 v[64:67], v105 offset:35200
	s_nop 1
	ds_read_b128 v[68:71], v105 offset:35264
	ds_read_b128 v[114:117], v106 offset:448
	v_lshl_add_u64 v[24:25], s[24:25], 0, v[20:21]
	v_lshl_add_u64 v[28:29], s[26:27], 0, v[20:21]
	v_mfma_f32_16x16x32_bf16 v[8:11], v[142:145], v[122:125], v[138:141]
	v_lshl_add_u64 v[26:27], s[28:29], 0, v[20:21]
	v_lshl_add_u64 v[30:31], s[30:31], 0, v[20:21]
	s_waitcnt lgkmcnt(2)
	v_mfma_f32_16x16x32_bf16 v[4:7], v[48:51], v[64:67], v[4:7]
	ds_read_b128 v[48:51], v106 offset:8832
	ds_read_b128 v[118:121], v106 offset:8896
	v_mfma_f32_16x16x32_bf16 v[20:23], v[178:181], v[122:125], v[146:149]
	s_waitcnt lgkmcnt(1)
	v_mfma_f32_16x16x32_bf16 v[8:11], v[48:51], v[64:67], v[8:11]
	ds_read_b128 v[48:51], v106 offset:17280
	ds_read_b128 v[122:125], v106 offset:17344
	s_waitcnt lgkmcnt(1)
	v_mfma_f32_16x16x32_bf16 v[20:23], v[48:51], v[64:67], v[20:23]
	ds_read_b128 v[48:51], v106 offset:25728
	ds_read_b128 v[134:137], v106 offset:25792
	s_waitcnt lgkmcnt(1)
	v_mfma_f32_16x16x32_bf16 v[48:51], v[48:51], v[64:67], v[60:63]
	global_load_dwordx4 v[64:67], v[92:93], off offset:64
	s_waitcnt vmcnt(0)
	v_add_f32_e32 v43, v43, v67
	global_load_dwordx4 v[60:63], v[92:93], off
	v_mfma_f32_16x16x32_bf16 v[4:7], v[114:117], v[68:71], v[4:7]
	global_load_dwordx4 v[114:117], v[92:93], off offset:128
	v_mul_f32_e32 v43, 0xbfb8aa3b, v43
	v_exp_f32_e32 v43, v43
	v_mfma_f32_16x16x32_bf16 v[8:11], v[118:121], v[68:71], v[8:11]
	global_load_dwordx4 v[118:121], v[92:93], off offset:192
	s_nop 2
	v_cvt_pk_bf16_f32 v4, v4, v5
	v_cvt_pk_bf16_f32 v5, v6, v7
	v_mfma_f32_16x16x32_bf16 v[20:23], v[122:125], v[68:71], v[20:23]
	v_add_f32_e32 v40, v40, v64
	v_cvt_pk_bf16_f32 v6, v8, v9
	v_add_f32_e32 v41, v41, v65
	s_waitcnt lgkmcnt(0)
	v_mfma_f32_16x16x32_bf16 v[48:51], v[134:137], v[68:71], v[48:51]
	v_add_f32_e32 v42, v42, v66
	s_nop 1
	v_cvt_pk_bf16_f32 v8, v20, v21
	v_cvt_pk_bf16_f32 v9, v22, v23
	v_cvt_pk_bf16_f32 v7, v10, v11
	v_mul_f32_e32 v40, 0xbfb8aa3b, v40
	s_nop 0
	v_cvt_pk_bf16_f32 v10, v48, v49
	v_cvt_pk_bf16_f32 v11, v50, v51
	v_mul_f32_e32 v41, 0xbfb8aa3b, v41
	v_mul_f32_e32 v42, 0xbfb8aa3b, v42
	v_exp_f32_e32 v40, v40
	v_exp_f32_e32 v41, v41
	v_exp_f32_e32 v42, v42
	v_add_f32_e32 v43, 1.0, v43
	v_rcp_f32_e32 v43, v43
	v_add_f32_e32 v40, 1.0, v40
	v_add_f32_e32 v41, 1.0, v41
	v_add_f32_e32 v42, 1.0, v42
	v_rcp_f32_e32 v40, v40
	v_rcp_f32_e32 v41, v41
	v_rcp_f32_e32 v42, v42
	v_mul_f32_e32 v43, 0xbf1b4598, v43
	v_mul_f32_e32 v43, 0x3fb8aa3b, v43
	v_mul_f32_e32 v40, 0xbf1b4598, v40
	v_mul_f32_e32 v41, 0xbf1b4598, v41
	v_mul_f32_e32 v42, 0xbf1b4598, v42
	v_mul_f32_e32 v40, 0x3fb8aa3b, v40
	v_mul_f32_e32 v41, 0x3fb8aa3b, v41
	v_mul_f32_e32 v42, 0x3fb8aa3b, v42
	s_waitcnt vmcnt(2)
	v_add_f32_e32 v20, v56, v60
	v_mul_f32_e32 v20, 0xbfb8aa3b, v20
	v_exp_f32_e32 v20, v20
	v_add_f32_e32 v21, v57, v61
	v_add_f32_e32 v22, v58, v62
	v_add_f32_e32 v23, v59, v63
	s_waitcnt vmcnt(1)
	v_add_f32_e32 v48, v52, v114
	v_add_f32_e32 v49, v53, v115
	v_add_f32_e32 v50, v54, v116
	v_add_f32_e32 v51, v55, v117
	s_waitcnt vmcnt(0)
	v_add_f32_e32 v36, v36, v118
	v_add_f32_e32 v37, v37, v119
	v_add_f32_e32 v38, v38, v120
	v_add_f32_e32 v39, v39, v121
	v_mul_f32_e32 v21, 0xbfb8aa3b, v21
	v_mul_f32_e32 v22, 0xbfb8aa3b, v22
	v_mul_f32_e32 v23, 0xbfb8aa3b, v23
	v_mul_f32_e32 v48, 0xbfb8aa3b, v48
	v_mul_f32_e32 v49, 0xbfb8aa3b, v49
	v_mul_f32_e32 v50, 0xbfb8aa3b, v50
	v_mul_f32_e32 v51, 0xbfb8aa3b, v51
	v_mul_f32_e32 v36, 0xbfb8aa3b, v36
	v_mul_f32_e32 v37, 0xbfb8aa3b, v37
	v_mul_f32_e32 v38, 0xbfb8aa3b, v38
	v_mul_f32_e32 v39, 0xbfb8aa3b, v39
	v_exp_f32_e32 v21, v21
	v_exp_f32_e32 v22, v22
	v_exp_f32_e32 v23, v23
	v_exp_f32_e32 v48, v48
	v_exp_f32_e32 v49, v49
	v_exp_f32_e32 v50, v50
	v_exp_f32_e32 v51, v51
	v_exp_f32_e32 v36, v36
	v_exp_f32_e32 v37, v37
	v_exp_f32_e32 v38, v38
	v_exp_f32_e32 v39, v39
	v_add_f32_e32 v20, 1.0, v20
	v_rcp_f32_e32 v20, v20
	v_add_f32_e32 v21, 1.0, v21
	v_add_f32_e32 v22, 1.0, v22
	v_add_f32_e32 v23, 1.0, v23
	v_add_f32_e32 v48, 1.0, v48
	v_add_f32_e32 v49, 1.0, v49
	v_add_f32_e32 v50, 1.0, v50
	v_add_f32_e32 v51, 1.0, v51
	v_add_f32_e32 v36, 1.0, v36
	v_add_f32_e32 v37, 1.0, v37
	v_add_f32_e32 v38, 1.0, v38
	v_add_f32_e32 v39, 1.0, v39
	v_rcp_f32_e32 v21, v21
	v_rcp_f32_e32 v22, v22
	v_rcp_f32_e32 v23, v23
	v_rcp_f32_e32 v48, v48
	v_rcp_f32_e32 v49, v49
	v_rcp_f32_e32 v50, v50
	v_rcp_f32_e32 v51, v51
	v_rcp_f32_e32 v36, v36
	v_rcp_f32_e32 v37, v37
	v_rcp_f32_e32 v38, v38
	v_rcp_f32_e32 v39, v39
	v_mul_f32_e32 v20, 0xbf1b4598, v20
	v_mul_f32_e32 v20, 0x3fb8aa3b, v20
	v_exp_f32_e32 v56, v20
	v_exp_f32_e32 v57, v43
	v_mul_f32_e32 v21, 0xbf1b4598, v21
	v_mul_f32_e32 v22, 0xbf1b4598, v22
	v_mul_f32_e32 v23, 0xbf1b4598, v23
	v_mul_f32_e32 v48, 0xbf1b4598, v48
	v_mul_f32_e32 v49, 0xbf1b4598, v49
	v_mul_f32_e32 v50, 0xbf1b4598, v50
	v_mul_f32_e32 v51, 0xbf1b4598, v51
	v_mul_f32_e32 v36, 0xbf1b4598, v36
	v_mul_f32_e32 v37, 0xbf1b4598, v37
	v_mul_f32_e32 v38, 0xbf1b4598, v38
	v_mul_f32_e32 v39, 0xbf1b4598, v39
	v_mul_f32_e32 v21, 0x3fb8aa3b, v21
	v_mul_f32_e32 v22, 0x3fb8aa3b, v22
	v_mul_f32_e32 v23, 0x3fb8aa3b, v23
	v_mul_f32_e32 v48, 0x3fb8aa3b, v48
	v_mul_f32_e32 v49, 0x3fb8aa3b, v49
	v_mul_f32_e32 v50, 0x3fb8aa3b, v50
	v_mul_f32_e32 v51, 0x3fb8aa3b, v51
	v_mul_f32_e32 v52, 0x3fb8aa3b, v36
	v_mul_f32_e32 v53, 0x3fb8aa3b, v37
	v_mul_f32_e32 v54, 0x3fb8aa3b, v38
	v_mul_f32_e32 v55, 0x3fb8aa3b, v39
	v_exp_f32_e32 v20, v21
	v_exp_f32_e32 v21, v22
	v_exp_f32_e32 v22, v23
	v_exp_f32_e32 v23, v40
	v_exp_f32_e32 v36, v41
	v_exp_f32_e32 v37, v42
	v_exp_f32_e32 v38, v48
; __device__ __forceinline__ float sigmoidf_(float x) { return __builtin_amdgcn_rcpf(1.0f + __expf(-x)); }
; __device__ __forceinline__ void phase2_main(const Params& p) {
;     ...
;             for (int n = 0; n < 4; ++n) {
;                 const f32x4 db = *(const f32x4*)(p.in[7] + h * 64 + n * 16 + fq * 4);
; #pragma unroll
;                 for (int j = 0; j < 4; ++j) {
;                     const float e = sigmoidf_(db[j] + acc[n][j]) * 0.60653065971f;
;                     wo[n >> 1][(n & 1) * 4 + j] = (_Float16)(1.0f - __expf(-e));
;                 }
;             }
;             *(h16x8*)(SI + SI_W * 64 + pb) = wo[0]; *(h16x8*)(SI + SI_W * 64 + pb + 8) = wo[1];
;         }
;         lora(std::integral_constant<int, 64>{}, std::integral_constant<int, 2>{});
;         {
;             const _Float16* up = ur + h * 64 + fq * 16;
;             const _Float16* upp = t > 0 ? up - RWS : up;
;             h16x8 kc[2], rc[2], vc[2], kp[2], rp[2], vp[2];
; #pragma unroll
;             for (int i = 0; i < 2; ++i) {
;                 rc[i] = *(const h16x8*)(up + i * 8); kc[i] = *(const h16x8*)(up + 512 + i * 8); vc[i] = *(const h16x8*)(up + 1024 + i * 8);
;                 rp[i] = *(const h16x8*)(upp + i * 8); kp[i] = *(const h16x8*)(upp + 512 + i * 8); vp[i] = *(const h16x8*)(upp + 1024 + i * 8);
;             }
	v_exp_f32_e32 v39, v49
	v_exp_f32_e32 v40, v50
	v_exp_f32_e32 v41, v51
	v_exp_f32_e32 v42, v52
	v_exp_f32_e32 v43, v53
	v_exp_f32_e32 v48, v54
	v_exp_f32_e32 v49, v55
	v_sub_f32_e32 v50, 1.0, v56
	v_sub_f32_e32 v51, 1.0, v57
	v_cvt_f16_f32_e32 v50, v50
	v_cvt_f16_f32_e32 v51, v51
	v_pk_add_f32 v[20:21], v[20:21], 1.0 op_sel_hi:[1,0] neg_lo:[1,0] neg_hi:[1,0]
	v_pk_add_f32 v[22:23], v[22:23], 1.0 op_sel_hi:[1,0] neg_lo:[1,0] neg_hi:[1,0]
	v_pk_add_f32 v[36:37], v[36:37], 1.0 op_sel_hi:[1,0] neg_lo:[1,0] neg_hi:[1,0]
	v_pk_add_f32 v[38:39], v[38:39], 1.0 op_sel_hi:[1,0] neg_lo:[1,0] neg_hi:[1,0]
	v_pk_add_f32 v[40:41], v[40:41], 1.0 op_sel_hi:[1,0] neg_lo:[1,0] neg_hi:[1,0]
	v_pk_add_f32 v[42:43], v[42:43], 1.0 op_sel_hi:[1,0] neg_lo:[1,0] neg_hi:[1,0]
	v_pk_add_f32 v[48:49], v[48:49], 1.0 op_sel_hi:[1,0] neg_lo:[1,0] neg_hi:[1,0]
	v_cvt_pk_f16_f32 v52, v20, v21
	v_cvt_pk_f16_f32 v53, v22, v23
	v_cvt_pk_f16_f32 v54, v36, v37
	v_cvt_pk_f16_f32 v20, v38, v39
	v_cvt_pk_f16_f32 v21, v40, v41
	v_cvt_pk_f16_f32 v22, v42, v43
	v_cvt_pk_f16_f32 v23, v48, v49
	v_alignbit_b32 v37, v53, v52, 16
	v_alignbit_b32 v38, v54, v53, 16
	v_pack_b32_f16 v36, v50, v52
	v_alignbit_b32 v39, v51, v54, 16
	global_store_dwordx4 v[154:155], v[20:23], off offset:16 nt
	global_store_dwordx4 v[154:155], v[36:39], off nt
	global_load_dwordx4 v[38:41], v[126:127], off
	s_nop 0
	global_load_dwordx4 v[48:51], v[150:151], off
	global_load_dwordx4 v[52:55], v[126:127], off offset:2048
	global_load_dwordx4 v[56:59], v[150:151], off offset:2048
	global_load_dwordx4 v[60:63], v[94:95], off
	global_load_dwordx4 v[20:23], v[126:127], off offset:2064
	global_load_dwordx4 v[64:67], v[150:151], off offset:2064
	global_load_dwordx4 v[68:71], v[126:127], off offset:16
	global_load_dwordx4 v[114:117], v[150:151], off offset:16
	global_load_dwordx4 v[118:121], v[126:127], off offset:1024
	global_load_dwordx4 v[122:125], v[150:151], off offset:1024
	global_load_dwordx4 v[134:137], v[126:127], off offset:1040
	global_load_dwordx4 v[138:141], v[150:151], off offset:1040
	global_load_dwordx4 v[142:145], v[82:83], off offset:2048
	global_load_dwordx4 v[146:149], v[82:83], off
	global_load_dwordx4 v[178:181], v[84:85], off
	global_load_dwordx4 v[182:185], v[96:97], off
	s_waitcnt vmcnt(16)
	v_cvt_f32_f16_e32 v113, v38
	s_waitcnt vmcnt(15)
	v_cvt_f32_f16_e32 v129, v48
	s_waitcnt vmcnt(14)
	v_cvt_f32_f16_e32 v131, v52
	s_waitcnt vmcnt(13)
	v_cvt_f32_f16_e32 v152, v56
	s_waitcnt vmcnt(12)
	v_add_f32_e32 v60, v44, v60
	v_add_f32_e32 v61, v45, v61
	v_cvt_f32_f16_e32 v44, v53
	v_cvt_f32_f16_sdwa v45, v53 dst_sel:DWORD dst_unused:UNUSED_PAD src0_sel:WORD_1
	v_cvt_f32_f16_sdwa v53, v57 dst_sel:DWORD dst_unused:UNUSED_PAD src0_sel:WORD_1
	v_cvt_f32_f16_e32 v57, v57
	v_cvt_f32_f16_sdwa v56, v56 dst_sel:DWORD dst_unused:UNUSED_PAD src0_sel:WORD_1
	v_cvt_f32_f16_sdwa v194, v58 dst_sel:DWORD dst_unused:UNUSED_PAD src0_sel:WORD_1
	v_cvt_f32_f16_e32 v58, v58
	v_cvt_f32_f16_sdwa v195, v51 dst_sel:DWORD dst_unused:UNUSED_PAD src0_sel:WORD_1
	v_cvt_f32_f16_e32 v196, v51
	s_waitcnt vmcnt(8)
	v_cvt_f32_f16_sdwa v201, v114 dst_sel:DWORD dst_unused:UNUSED_PAD src0_sel:WORD_1
	v_cvt_f32_f16_e32 v202, v114
	v_cvt_f32_f16_sdwa v203, v115 dst_sel:DWORD dst_unused:UNUSED_PAD src0_sel:WORD_1
	v_cvt_f32_f16_e32 v204, v115
	v_cvt_f32_f16_e32 v114, v21
	v_cvt_f32_f16_sdwa v115, v21 dst_sel:DWORD dst_unused:UNUSED_PAD src0_sel:WORD_1
	v_cvt_f32_f16_sdwa v21, v65 dst_sel:DWORD dst_unused:UNUSED_PAD src0_sel:WORD_1
	v_cvt_f32_f16_sdwa v210, v52 dst_sel:DWORD dst_unused:UNUSED_PAD src0_sel:WORD_1
	v_add_f32_e32 v189, v46, v62
	v_cvt_f32_f16_e32 v42, v39
	v_cvt_f32_f16_sdwa v43, v39 dst_sel:DWORD dst_unused:UNUSED_PAD src0_sel:WORD_1
	v_cvt_f32_f16_sdwa v39, v49 dst_sel:DWORD dst_unused:UNUSED_PAD src0_sel:WORD_1
	v_cvt_f32_f16_e32 v190, v49
	v_add_f32_e32 v191, v47, v63
	v_cvt_f32_f16_e32 v150, v41
	v_cvt_f32_f16_sdwa v151, v41 dst_sel:DWORD dst_unused:UNUSED_PAD src0_sel:WORD_1
	v_cvt_f32_f16_sdwa v197, v59 dst_sel:DWORD dst_unused:UNUSED_PAD src0_sel:WORD_1
	s_waitcnt vmcnt(6)
	v_cvt_f32_f16_e32 v216, v122
	v_cvt_f32_f16_sdwa v217, v123 dst_sel:DWORD dst_unused:UNUSED_PAD src0_sel:WORD_1
	v_cvt_f32_f16_sdwa v192, v50 dst_sel:DWORD dst_unused:UNUSED_PAD src0_sel:WORD_1
	v_cvt_f32_f16_e32 v193, v50
	v_cvt_f32_f16_sdwa v211, v117 dst_sel:DWORD dst_unused:UNUSED_PAD src0_sel:WORD_1
	v_cvt_f32_f16_sdwa v215, v122 dst_sel:DWORD dst_unused:UNUSED_PAD src0_sel:WORD_1
	v_cvt_f32_f16_e32 v218, v123
	v_mul_f32_e32 v50, 0xbfb8aa3b, v189
	v_mul_f32_e32 v51, 0xbfb8aa3b, v191
	v_cvt_f32_f16_sdwa v188, v48 dst_sel:DWORD dst_unused:UNUSED_PAD src0_sel:WORD_1
	v_cvt_f32_f16_e32 v62, v40
	v_cvt_f32_f16_sdwa v63, v40 dst_sel:DWORD dst_unused:UNUSED_PAD src0_sel:WORD_1
	v_cvt_f32_f16_e32 v126, v54
	v_cvt_f32_f16_sdwa v127, v54 dst_sel:DWORD dst_unused:UNUSED_PAD src0_sel:WORD_1
	v_cvt_f32_f16_e32 v198, v59
	v_cvt_f32_f16_sdwa v200, v64 dst_sel:DWORD dst_unused:UNUSED_PAD src0_sel:WORD_1
	v_cvt_f32_f16_e32 v212, v117
	v_cvt_f32_f16_sdwa v213, v67 dst_sel:DWORD dst_unused:UNUSED_PAD src0_sel:WORD_1
	v_cvt_f32_f16_e32 v214, v67
	v_cvt_f32_f16_e32 v46, v118
	v_cvt_f32_f16_sdwa v47, v118 dst_sel:DWORD dst_unused:UNUSED_PAD src0_sel:WORD_1
	v_cvt_f32_f16_e32 v48, v119
	v_cvt_f32_f16_sdwa v49, v119 dst_sel:DWORD dst_unused:UNUSED_PAD src0_sel:WORD_1
	v_exp_f32_e32 v235, v50
	v_exp_f32_e32 v236, v51
	v_cndmask_b32_e64 v129, 0, v129, s[0:1]
	v_cndmask_b32_e64 v152, 0, v152, s[0:1]
	v_cndmask_b32_e64 v50, 0, v57, s[0:1]
	v_cndmask_b32_e64 v51, 0, v53, s[0:1]
	v_cvt_f32_f16_sdwa v177, v38 dst_sel:DWORD dst_unused:UNUSED_PAD src0_sel:WORD_1
	v_cvt_f32_f16_e32 v154, v55
	v_cvt_f32_f16_sdwa v155, v55 dst_sel:DWORD dst_unused:UNUSED_PAD src0_sel:WORD_1
	v_cvt_f32_f16_e32 v199, v64
	v_cvt_f32_f16_sdwa v221, v20 dst_sel:DWORD dst_unused:UNUSED_PAD src0_sel:WORD_1
	v_cvt_f32_f16_sdwa v219, v124 dst_sel:DWORD dst_unused:UNUSED_PAD src0_sel:WORD_1
	s_waitcnt vmcnt(4)
; __device__ __forceinline__ float sigmoidf_(float x) { return __builtin_amdgcn_rcpf(1.0f + __expf(-x)); }
; __device__ __forceinline__ void phase2_main(const Params& p) {
;     ...
;             float kv[4][4], av[4][4], kkr[4][4]; float ss = 0.f;
;             h16x8 ro[2];
; #pragma unroll
;             for (int n = 0; n < 4; ++n) {
;                 const int c = n * 16 + fq * 4, c512 = h * 64 + c;
;                 const f32x4 muk = *(const f32x4*)(mu + 512 + c512), mur = *(const f32x4*)(mu + c512), muv = *(const f32x4*)(mu + 1024 + c512);
;                 const f32x4 ab = *(const f32x4*)(p.in[9] + c512), kkw = *(const f32x4*)(p.in[11] + c512);
;                 h16x4 vo;
; #pragma unroll
;                 for (int j = 0; j < 4; ++j) {
;                     const int i = n >> 1, e = (n & 1) * 4 + j;
;                     const float kcf = (float)kc[i][e], kpf = t > 0 ? (float)kp[i][e] : 0.f;
;                     const float rcf = (float)rc[i][e], rpf = t > 0 ? (float)rp[i][e] : 0.f;
;                     const float vcf = (float)vc[i][e], vpf = t > 0 ? (float)vp[i][e] : 0.f;
;                     kv[n][j] = kcf + muk[j] * (kpf - kcf);
;                     ro[i][e] = (_Float16)(rcf + mur[j] * (rpf - rcf));
;                     vo[j] = (_Float16)(vcf + muv[j] * (vpf - vcf));
;                     av[n][j] = sigmoidf_(ab[j] + acc[n][j]);
;                     kkr[n][j] = kv[n][j] * kkw[j];
;                     ss += kkr[n][j] * kkr[n][j];
;                 }
;                 *(h16x4*)(SI + SI_V * 64 + base + c) = vo;
;             }
	v_cvt_f32_f16_sdwa v227, v139 dst_sel:DWORD dst_unused:UNUSED_PAD src0_sel:WORD_1
	v_cvt_f32_f16_e32 v228, v139
	v_mul_f32_e32 v40, 0xbfb8aa3b, v60
	v_mul_f32_e32 v41, 0xbfb8aa3b, v61
	v_cndmask_b32_e64 v238, 0, v56, s[0:1]
	v_cndmask_b32_e64 v56, 0, v58, s[0:1]
	v_cndmask_b32_e64 v58, 0, v196, s[0:1]
	v_cndmask_b32_e64 v59, 0, v195, s[0:1]
	v_cndmask_b32_e64 v139, 0, v21, s[0:1]
	v_sub_f32_e32 v21, v129, v113
	v_sub_f32_e32 v113, v152, v131
	v_pk_add_f32 v[50:51], v[50:51], v[44:45] neg_lo:[0,1] neg_hi:[0,1]
	v_exp_f32_e32 v233, v40
	v_exp_f32_e32 v234, v41
	v_cndmask_b32_e64 v40, 0, v190, s[0:1]
	v_cndmask_b32_e64 v41, 0, v39, s[0:1]
	v_cndmask_b32_e64 v57, 0, v194, s[0:1]
	v_cndmask_b32_e64 v61, 0, v197, s[0:1]
	v_cndmask_b32_e64 v194, 0, v216, s[0:1]
	v_cndmask_b32_e64 v197, 0, v217, s[0:1]
	v_sub_f32_e32 v131, v238, v210
	v_pk_add_f32 v[216:217], v[58:59], v[150:151] neg_lo:[0,1] neg_hi:[0,1]
	s_waitcnt vmcnt(1)
	v_fma_mixlo_f16 v58, v113, v178, v52 op_sel_hi:[0,0,1]
	v_pk_fma_f32 v[44:45], v[50:51], v[180:181], v[44:45]
	v_cndmask_b32_e64 v54, 0, v193, s[0:1]
	v_cndmask_b32_e64 v55, 0, v192, s[0:1]
	v_cndmask_b32_e64 v191, 0, v211, s[0:1]
	v_cndmask_b32_e64 v195, 0, v215, s[0:1]
	v_cndmask_b32_e64 v196, 0, v218, s[0:1]
	v_pk_add_f32 v[210:211], v[40:41], v[42:43] neg_lo:[0,1] neg_hi:[0,1]
	v_fma_mixhi_f16 v58, v131, v179, v52 op_sel:[0,0,1] op_sel_hi:[0,0,1]
	v_cvt_pk_f16_f32 v59, v44, v45
	v_cndmask_b32_e64 v237, 0, v188, s[0:1]
	v_cndmask_b32_e64 v60, 0, v198, s[0:1]
	v_cndmask_b32_e64 v53, 0, v200, s[0:1]
	v_cndmask_b32_e64 v190, 0, v212, s[0:1]
	v_cndmask_b32_e64 v192, 0, v214, s[0:1]
	v_cndmask_b32_e64 v193, 0, v213, s[0:1]
	v_pk_add_f32 v[212:213], v[54:55], v[62:63] neg_lo:[0,1] neg_hi:[0,1]
	v_pk_add_f32 v[214:215], v[56:57], v[126:127] neg_lo:[0,1] neg_hi:[0,1]
	v_pk_add_f32 v[54:55], v[194:195], v[46:47] neg_lo:[0,1] neg_hi:[0,1]
	v_pk_add_f32 v[56:57], v[196:197], v[48:49] neg_lo:[0,1] neg_hi:[0,1]
	v_add_f32_e32 v41, 1.0, v235
	v_pk_fma_f32 v[42:43], v[210:211], v[148:149], v[42:43]
	v_add_f32_e32 v50, 1.0, v236
	global_store_dwordx2 v[32:33], v[58:59], off nt
	v_cndmask_b32_e64 v39, 0, v199, s[0:1]
	v_cndmask_b32_e64 v199, 0, v219, s[0:1]
	v_sub_f32_e32 v129, v237, v177
	v_pk_add_f32 v[218:219], v[60:61], v[154:155] neg_lo:[0,1] neg_hi:[0,1]
	v_sub_f32_e32 v177, v53, v221
	v_pk_fma_f32 v[142:143], v[54:55], v[142:143], v[46:47]
	v_pk_fma_f32 v[144:145], v[56:57], v[144:145], v[48:49]
	v_rcp_f32_e32 v178, v41
	v_cvt_pk_f16_f32 v41, v42, v43
	v_rcp_f32_e32 v179, v50
	global_load_dwordx4 v[42:45], v[94:95], off offset:64
	global_load_dwordx4 v[46:49], v[82:83], off offset:64
	global_load_dwordx4 v[50:53], v[86:87], off
	global_load_dwordx4 v[54:57], v[82:83], off offset:2112
	global_load_dwordx4 v[58:61], v[96:97], off offset:64
	v_cvt_f32_f16_e32 v222, v124
	v_cvt_f32_f16_sdwa v208, v66 dst_sel:DWORD dst_unused:UNUSED_PAD src0_sel:WORD_1
	v_cvt_f32_f16_e32 v209, v66
	v_cvt_f32_f16_e32 v66, v120
	v_cvt_f32_f16_sdwa v67, v120 dst_sel:DWORD dst_unused:UNUSED_PAD src0_sel:WORD_1
	v_cvt_f32_f16_sdwa v223, v125 dst_sel:DWORD dst_unused:UNUSED_PAD src0_sel:WORD_1
	v_cvt_f32_f16_e32 v224, v125
	v_cvt_f32_f16_sdwa v206, v116 dst_sel:DWORD dst_unused:UNUSED_PAD src0_sel:WORD_1
	v_cvt_f32_f16_e32 v207, v116
	v_cvt_f32_f16_e32 v116, v121
	v_cvt_f32_f16_sdwa v117, v121 dst_sel:DWORD dst_unused:UNUSED_PAD src0_sel:WORD_1
	v_cndmask_b32_e64 v198, 0, v222, s[0:1]
	v_cvt_f32_f16_e32 v120, v135
	v_cvt_f32_f16_sdwa v121, v135 dst_sel:DWORD dst_unused:UNUSED_PAD src0_sel:WORD_1
	v_cndmask_b32_e64 v135, 0, v201, s[0:1]
	v_cndmask_b32_e64 v200, 0, v224, s[0:1]
	v_cndmask_b32_e64 v201, 0, v223, s[0:1]
	v_pk_add_f32 v[194:195], v[198:199], v[66:67] neg_lo:[0,1] neg_hi:[0,1]
	v_pk_add_f32 v[196:197], v[200:201], v[116:117] neg_lo:[0,1] neg_hi:[0,1]
	v_fma_mixlo_f16 v40, v21, v146, v38 op_sel_hi:[0,0,1]
	v_fma_mixhi_f16 v40, v129, v147, v38 op_sel:[0,0,1] op_sel_hi:[0,0,1]
	v_cvt_f32_f16_e32 v220, v20
	v_cvt_f32_f16_e32 v205, v65
	v_add_f32_e32 v21, 1.0, v233
	s_waitcnt vmcnt(6)
	v_pk_mul_f32 v[146:147], v[144:145], v[184:185]
	v_sub_f32_e32 v152, v39, v220
	v_add_f32_e32 v39, 1.0, v234
	v_rcp_f32_e32 v149, v39
	v_pk_mul_f32 v[38:39], v[142:143], v[182:183]
	v_rcp_f32_e32 v148, v21
	v_pk_mul_f32 v[180:181], v[38:39], v[38:39]
	v_pk_mul_f32 v[182:183], v[146:147], v[146:147]
	v_add_f32_e32 v21, v180, v181
	v_cvt_f32_f16_e32 v186, v68
	v_cvt_f32_f16_sdwa v187, v68 dst_sel:DWORD dst_unused:UNUSED_PAD src0_sel:WORD_1
	v_cvt_f32_f16_e32 v68, v69
	v_cvt_f32_f16_sdwa v69, v69 dst_sel:DWORD dst_unused:UNUSED_PAD src0_sel:WORD_1
	v_cvt_f32_f16_sdwa v225, v138 dst_sel:DWORD dst_unused:UNUSED_PAD src0_sel:WORD_1
	v_cvt_f32_f16_e32 v226, v138
	v_add_f32_e32 v21, v182, v21
	v_cvt_f32_f16_e32 v118, v134
	v_cvt_f32_f16_sdwa v119, v134 dst_sel:DWORD dst_unused:UNUSED_PAD src0_sel:WORD_1
	v_cndmask_b32_e64 v138, 0, v205, s[0:1]
	v_add_f32_e32 v21, v183, v21
	v_pk_add_f32 v[138:139], v[138:139], v[114:115] neg_lo:[0,1] neg_hi:[0,1]
	v_cvt_f32_f16_e32 v122, v136
	v_cvt_f32_f16_sdwa v123, v136 dst_sel:DWORD dst_unused:UNUSED_PAD src0_sel:WORD_1
	v_cvt_f32_f16_e32 v124, v137
	v_cvt_f32_f16_sdwa v125, v137 dst_sel:DWORD dst_unused:UNUSED_PAD src0_sel:WORD_1
	v_cndmask_b32_e64 v134, 0, v202, s[0:1]
	v_cndmask_b32_e64 v136, 0, v204, s[0:1]
	v_cndmask_b32_e64 v137, 0, v203, s[0:1]
	v_cndmask_b32_e64 v202, 0, v226, s[0:1]
	v_cndmask_b32_e64 v203, 0, v225, s[0:1]
	v_cndmask_b32_e64 v204, 0, v228, s[0:1]
	v_cndmask_b32_e64 v205, 0, v227, s[0:1]
	v_pk_add_f32 v[134:135], v[134:135], v[186:187] neg_lo:[0,1] neg_hi:[0,1]
	v_pk_add_f32 v[136:137], v[136:137], v[68:69] neg_lo:[0,1] neg_hi:[0,1]
	v_pk_add_f32 v[198:199], v[202:203], v[118:119] neg_lo:[0,1] neg_hi:[0,1]
	v_pk_add_f32 v[200:201], v[204:205], v[120:121] neg_lo:[0,1] neg_hi:[0,1]
	v_cvt_f32_f16_e32 v36, v70
	v_cvt_f32_f16_sdwa v37, v70 dst_sel:DWORD dst_unused:UNUSED_PAD src0_sel:WORD_1
	v_cvt_f32_f16_e32 v64, v22
	v_cvt_f32_f16_sdwa v65, v22 dst_sel:DWORD dst_unused:UNUSED_PAD src0_sel:WORD_1
	v_cvt_f32_f16_e32 v70, v71
	v_cvt_f32_f16_sdwa v71, v71 dst_sel:DWORD dst_unused:UNUSED_PAD src0_sel:WORD_1
	v_cvt_f32_f16_e32 v22, v23
	v_cvt_f32_f16_sdwa v23, v23 dst_sel:DWORD dst_unused:UNUSED_PAD src0_sel:WORD_1
	v_cvt_f32_f16_sdwa v229, v140 dst_sel:DWORD dst_unused:UNUSED_PAD src0_sel:WORD_1
	v_cvt_f32_f16_e32 v230, v140
	v_cvt_f32_f16_sdwa v231, v141 dst_sel:DWORD dst_unused:UNUSED_PAD src0_sel:WORD_1
	v_cvt_f32_f16_e32 v232, v141
	v_cndmask_b32_e64 v140, 0, v207, s[0:1]
	v_cndmask_b32_e64 v141, 0, v206, s[0:1]
	v_cndmask_b32_e64 v188, 0, v209, s[0:1]
	s_waitcnt vmcnt(4)
; __device__ __forceinline__ float sigmoidf_(float x) { return __builtin_amdgcn_rcpf(1.0f + __expf(-x)); }
; __device__ __forceinline__ void phase2_main(const Params& p) {
;     ...
;             for (int n = 0; n < 4; ++n) {
;                 const int c = n * 16 + fq * 4, c512 = h * 64 + c;
;                 const f32x4 muk = *(const f32x4*)(mu + 512 + c512), mur = *(const f32x4*)(mu + c512), muv = *(const f32x4*)(mu + 1024 + c512);
;                 const f32x4 ab = *(const f32x4*)(p.in[9] + c512), kkw = *(const f32x4*)(p.in[11] + c512);
;                 h16x4 vo;
; #pragma unroll
;                 for (int j = 0; j < 4; ++j) {
;                     const int i = n >> 1, e = (n & 1) * 4 + j;
;                     const float kcf = (float)kc[i][e], kpf = t > 0 ? (float)kp[i][e] : 0.f;
;                     const float rcf = (float)rc[i][e], rpf = t > 0 ? (float)rp[i][e] : 0.f;
;                     const float vcf = (float)vc[i][e], vpf = t > 0 ? (float)vp[i][e] : 0.f;
;                     kv[n][j] = kcf + muk[j] * (kpf - kcf);
;                     ro[i][e] = (_Float16)(rcf + mur[j] * (rpf - rcf));
;                     vo[j] = (_Float16)(vcf + muv[j] * (vpf - vcf));
;                     av[n][j] = sigmoidf_(ab[j] + acc[n][j]);
;                     kkr[n][j] = kv[n][j] * kkw[j];
;                     ss += kkr[n][j] * kkr[n][j];
;                 }
;                 *(h16x4*)(SI + SI_V * 64 + base + c) = vo;
;             }
	v_add_f32_e32 v42, v16, v42
	v_add_f32_e32 v43, v17, v43
	s_waitcnt vmcnt(2)
	v_pk_fma_f32 v[50:51], v[214:215], v[50:51], v[126:127]
	v_pk_fma_f32 v[16:17], v[216:217], v[48:49], v[150:151]
	v_pk_fma_f32 v[48:49], v[218:219], v[52:53], v[154:155]
	v_pk_fma_f32 v[46:47], v[212:213], v[46:47], v[62:63]
	v_add_f32_e32 v44, v18, v44
	v_add_f32_e32 v45, v19, v45
	v_cvt_pk_f16_f32 v18, v50, v51
	v_cvt_pk_f16_f32 v19, v48, v49
	s_waitcnt vmcnt(1)
	v_pk_fma_f32 v[62:63], v[194:195], v[54:55], v[66:67]
	v_mul_f32_e32 v52, 0xbfb8aa3b, v42
	v_cvt_pk_f16_f32 v42, v46, v47
	v_mul_f32_e32 v46, 0xbfb8aa3b, v43
	v_mul_f32_e32 v44, 0xbfb8aa3b, v44
	v_cvt_pk_f16_f32 v43, v16, v17
	v_mul_f32_e32 v16, 0xbfb8aa3b, v45
	global_store_dwordx2 v[32:33], v[18:19], off offset:32 nt
	v_pk_fma_f32 v[66:67], v[196:197], v[56:57], v[116:117]
	s_waitcnt vmcnt(1)
	v_pk_mul_f32 v[116:117], v[62:63], v[58:59]
	v_exp_f32_e32 v113, v52
	v_exp_f32_e32 v129, v46
	v_exp_f32_e32 v131, v44
	v_exp_f32_e32 v154, v16
	global_load_dwordx4 v[16:19], v[88:89], off
	global_load_dwordx4 v[44:47], v[94:95], off offset:128
	global_load_dwordx4 v[48:51], v[82:83], off offset:128
	global_load_dwordx4 v[52:55], v[82:83], off offset:2176
	global_load_dwordx4 v[56:59], v[96:97], off offset:128
	v_pk_mul_f32 v[126:127], v[116:117], v[116:117]
	v_pk_mul_f32 v[60:61], v[66:67], v[60:61]
	v_add_f32_e32 v21, v21, v126
	v_pk_mul_f32 v[150:151], v[60:61], v[60:61]
	v_add_f32_e32 v21, v127, v21
	v_add_f32_e32 v21, v150, v21
	v_add_f32_e32 v113, 1.0, v113
	v_add_f32_e32 v127, 1.0, v129
	v_add_f32_e32 v129, 1.0, v131
	v_add_f32_e32 v131, 1.0, v154
	v_add_f32_e32 v194, v151, v21
	v_rcp_f32_e32 v126, v113
	v_rcp_f32_e32 v150, v129
	v_rcp_f32_e32 v151, v131
	v_cndmask_b32_e64 v189, 0, v208, s[0:1]
	v_pk_add_f32 v[140:141], v[140:141], v[36:37] neg_lo:[0,1] neg_hi:[0,1]
	v_pk_add_f32 v[188:189], v[188:189], v[64:65] neg_lo:[0,1] neg_hi:[0,1]
	v_pk_add_f32 v[190:191], v[190:191], v[70:71] neg_lo:[0,1] neg_hi:[0,1]
	v_pk_add_f32 v[192:193], v[192:193], v[22:23] neg_lo:[0,1] neg_hi:[0,1]
	v_cndmask_b32_e64 v206, 0, v230, s[0:1]
	v_cndmask_b32_e64 v207, 0, v229, s[0:1]
	v_cndmask_b32_e64 v208, 0, v232, s[0:1]
	v_cndmask_b32_e64 v209, 0, v231, s[0:1]
	v_pk_add_f32 v[202:203], v[206:207], v[122:123] neg_lo:[0,1] neg_hi:[0,1]
	v_pk_add_f32 v[204:205], v[208:209], v[124:125] neg_lo:[0,1] neg_hi:[0,1]
	v_rcp_f32_e32 v127, v127
	v_pk_add_f32 v[180:181], v[148:149], -1.0 op_sel_hi:[1,0]
	v_pk_add_f32 v[184:185], v[178:179], -1.0 op_sel_hi:[1,0]
	v_pk_add_f32 v[182:183], v[150:151], -1.0 op_sel_hi:[1,0]
	v_pk_add_f32 v[154:155], v[126:127], -1.0 op_sel_hi:[1,0]
	v_cmp_lt_i32_e64 s[0:1], s53, v79
	s_or_b64 s[34:35], s[0:1], s[34:35]
	s_waitcnt vmcnt(4)
	v_fma_mixlo_f16 v16, v152, v16, v20 op_sel_hi:[0,0,1]
	v_pk_fma_f32 v[18:19], v[138:139], v[18:19], v[114:115]
	s_waitcnt vmcnt(3)
	v_add_f32_e32 v12, v12, v44
	v_add_f32_e32 v13, v13, v45
	v_add_f32_e32 v14, v14, v46
	v_add_f32_e32 v15, v15, v47
	v_fma_mixhi_f16 v16, v177, v17, v20 op_sel:[0,0,1] op_sel_hi:[0,0,1]
	v_cvt_pk_f16_f32 v17, v18, v19
	s_waitcnt vmcnt(2)
	v_pk_fma_f32 v[48:49], v[134:135], v[48:49], v[186:187]
	v_pk_fma_f32 v[44:45], v[136:137], v[50:51], v[68:69]
	v_mul_f32_e32 v21, 0xbfb8aa3b, v12
	v_mul_f32_e32 v20, 0xbfb8aa3b, v13
	v_mul_f32_e32 v14, 0xbfb8aa3b, v14
	v_mul_f32_e32 v15, 0xbfb8aa3b, v15
	global_store_dwordx2 v[32:33], v[16:17], off offset:64 nt
	s_waitcnt vmcnt(2)
	v_pk_fma_f32 v[68:69], v[198:199], v[52:53], v[118:119]
	v_pk_fma_f32 v[114:115], v[200:201], v[54:55], v[120:121]
	v_cvt_pk_f16_f32 v12, v48, v49
	v_cvt_pk_f16_f32 v13, v44, v45
	v_exp_f32_e32 v113, v21
	v_exp_f32_e32 v129, v20
	v_exp_f32_e32 v131, v14
	v_exp_f32_e32 v134, v15
	global_load_dwordx4 v[14:17], v[94:95], off offset:192
	global_load_dwordx4 v[18:21], v[82:83], off offset:192
	global_load_dwordx4 v[44:47], v[90:91], off
	global_load_dwordx4 v[48:51], v[82:83], off offset:2240
	global_load_dwordx4 v[52:55], v[96:97], off offset:192
	s_waitcnt vmcnt(6)
	v_pk_mul_f32 v[56:57], v[68:69], v[56:57]
	v_pk_mul_f32 v[58:59], v[114:115], v[58:59]
	v_pk_mul_f32 v[118:119], v[56:57], v[56:57]
	v_pk_mul_f32 v[120:121], v[58:59], v[58:59]
	v_add_f32_e32 v118, v194, v118
	v_add_f32_e32 v118, v119, v118
	v_add_f32_e32 v118, v120, v118
	v_add_f32_e32 v120, 1.0, v131
	v_add_f32_e32 v131, v121, v118
	v_add_f32_e32 v113, 1.0, v113
	v_add_f32_e32 v119, 1.0, v129
	v_add_f32_e32 v129, 1.0, v134
	v_rcp_f32_e32 v118, v113
	v_rcp_f32_e32 v119, v119
	v_rcp_f32_e32 v120, v120
	v_rcp_f32_e32 v121, v129
	v_pk_add_f32 v[134:135], v[118:119], -1.0 op_sel_hi:[1,0]
	v_pk_add_f32 v[136:137], v[120:121], -1.0 op_sel_hi:[1,0]
	s_waitcnt vmcnt(4)
	v_add_f32_e32 v14, v0, v14
	s_waitcnt vmcnt(3)
	v_pk_fma_f32 v[18:19], v[140:141], v[18:19], v[36:37]
	s_waitcnt vmcnt(2)
; __device__ __forceinline__ unsigned pk_bf16(float lo, float hi) { const f32x2 v = {lo, hi}; return __builtin_bit_cast(unsigned, __builtin_convertvector(v, b16x2)); }
; __device__ __forceinline__ void phase2_main(const Params& p) {
;     ...
;                 *(h16x4*)(SI + SI_V * 64 + base + c) = vo;
;             }
;             *(h16x8*)(SI + SI_R * 64 + pb) = ro[0]; *(h16x8*)(SI + SI_R * 64 + pb + 8) = ro[1];
;             ss += __shfl_xor(ss, 16); ss += __shfl_xor(ss, 32);
;             const float inv = fminf(__builtin_amdgcn_rsqf(ss), 1e12f);
;             h16x8 ko[2], kko[2], bo[2];
; #pragma unroll
;             for (int n = 0; n < 4; ++n) {
;                 const f32x4 ka = *(const f32x4*)(p.in[12] + h * 64 + n * 16 + fq * 4);
; #pragma unroll
;                 for (int j = 0; j < 4; ++j) {
;                     const int i = n >> 1, e = (n & 1) * 4 + j;
;                     const float kk = kkr[n][j] * inv;
;                     ko[i][e] = (_Float16)(kv[n][j] * (1.0f + (av[n][j] - 1.0f) * ka[j]));
;                     kko[i][e] = (_Float16)kk;
;                     bo[i][e] = (_Float16)(kk * av[n][j]);
;                 }
;             }
; #pragma unroll
;             for (int i = 0; i < 2; ++i) {
;                 *(h16x8*)(SI + SI_K * 64 + pb + i * 8) = ko[i]; *(h16x8*)(SI + SI_KK * 64 + pb + i * 8) = kko[i]; *(h16x8*)(SI + SI_B * 64 + pb + i * 8) = bo[i];
;             }
;         }
;         lora(std::integral_constant<int, 128>{}, std::integral_constant<int, 4>{});
;         {
;             u32x4 g0, g1;
;             g0.x = pk_bf16(acc[0][0], acc[0][1]); g0.y = pk_bf16(acc[0][2], acc[0][3]); g0.z = pk_bf16(acc[1][0], acc[1][1]); g0.w = pk_bf16(acc[1][2], acc[1][3]);
;             g1.x = pk_bf16(acc[2][0], acc[2][1]); g1.y = pk_bf16(acc[2][2], acc[2][3]); g1.z = pk_bf16(acc[3][0], acc[3][1]); g1.w = pk_bf16(acc[3][2], acc[3][3]);
;             *(u32x4*)((bf16_t*)SI + 6 * 64 + pb) = g0; *(u32x4*)((bf16_t*)SI + 6 * 64 + pb + 8) = g1;
	v_pk_fma_f32 v[36:37], v[188:189], v[44:45], v[64:65]
	v_add_f32_e32 v15, v1, v15
	v_pk_fma_f32 v[0:1], v[190:191], v[20:21], v[70:71]
	v_pk_fma_f32 v[20:21], v[192:193], v[46:47], v[22:23]
	v_add_f32_e32 v16, v2, v16
	v_add_f32_e32 v17, v3, v17
	v_cvt_pk_f16_f32 v2, v36, v37
	v_cvt_pk_f16_f32 v3, v20, v21
	s_waitcnt vmcnt(1)
	v_pk_fma_f32 v[44:45], v[202:203], v[48:49], v[122:123]
	v_mul_f32_e32 v22, 0xbfb8aa3b, v14
	v_cvt_pk_f16_f32 v14, v18, v19
	v_mul_f32_e32 v18, 0xbfb8aa3b, v15
	v_mul_f32_e32 v16, 0xbfb8aa3b, v16
	v_cvt_pk_f16_f32 v15, v0, v1
	v_mul_f32_e32 v0, 0xbfb8aa3b, v17
	global_store_dwordx2 v[32:33], v[2:3], off offset:96 nt
	global_store_dwordx4 v[34:35], v[40:43], off nt
	global_store_dwordx4 v[34:35], v[12:15], off offset:16 nt
	v_pk_fma_f32 v[46:47], v[204:205], v[50:51], v[124:125]
	s_waitcnt vmcnt(3)
	v_pk_mul_f32 v[36:37], v[44:45], v[52:53]
	v_exp_f32_e32 v50, v22
	v_exp_f32_e32 v51, v18
	v_exp_f32_e32 v52, v16
	v_exp_f32_e32 v53, v0
	global_load_dwordx4 v[0:3], v[98:99], off
	global_load_dwordx4 v[12:15], v[98:99], off offset:64
	global_load_dwordx4 v[16:19], v[98:99], off offset:128
	global_load_dwordx4 v[20:23], v[98:99], off offset:192
	v_pk_mul_f32 v[32:33], v[36:37], v[36:37]
	v_pk_mul_f32 v[48:49], v[46:47], v[54:55]
	v_add_f32_e32 v32, v131, v32
	v_pk_mul_f32 v[34:35], v[48:49], v[48:49]
	global_store_dwordx4 v[30:31], v[4:7], off nt
	global_store_dwordx4 v[30:31], v[8:11], off offset:16 nt
	s_waitcnt vmcnt(5)
	v_pk_fma_f32 v[0:1], v[180:181], v[0:1], 1.0 op_sel_hi:[1,1,0]
	v_add_f32_e32 v4, v33, v32
	v_add_f32_e32 v4, v34, v4
	v_add_f32_e32 v5, 1.0, v50
	v_add_f32_e32 v4, v35, v4
	v_rcp_f32_e32 v8, v5
	ds_bpermute_b32 v5, v112, v4
	v_add_f32_e32 v6, 1.0, v51
	v_add_f32_e32 v7, 1.0, v52
	v_add_f32_e32 v11, 1.0, v53
	v_rcp_f32_e32 v9, v6
	s_waitcnt lgkmcnt(0)
	v_add_f32_e32 v4, v4, v5
	ds_bpermute_b32 v5, v111, v4
	v_rcp_f32_e32 v10, v7
	v_rcp_f32_e32 v11, v11
	v_pk_add_f32 v[40:41], v[8:9], -1.0 op_sel_hi:[1,0]
	v_pk_fma_f32 v[2:3], v[184:185], v[2:3], 1.0 op_sel_hi:[1,1,0]
	s_waitcnt lgkmcnt(0)
	v_add_f32_e32 v4, v4, v5
	v_rsq_f32_e32 v4, v4
	v_pk_add_f32 v[42:43], v[10:11], -1.0 op_sel_hi:[1,0]
	v_pk_mul_f32 v[0:1], v[142:143], v[0:1]
	v_pk_mul_f32 v[2:3], v[144:145], v[2:3]
	v_min_f32_e32 v4, 0x5368d4a5, v4
	v_pk_mul_f32 v[30:31], v[38:39], v[4:5] op_sel_hi:[1,0]
	v_pk_mul_f32 v[32:33], v[146:147], v[4:5] op_sel_hi:[1,0]
	v_pk_mul_f32 v[34:35], v[116:117], v[4:5] op_sel_hi:[1,0]
	v_pk_mul_f32 v[6:7], v[60:61], v[4:5] op_sel_hi:[1,0]
	v_pk_mul_f32 v[38:39], v[56:57], v[4:5] op_sel_hi:[1,0]
	v_pk_mul_f32 v[50:51], v[58:59], v[4:5] op_sel_hi:[1,0]
	v_pk_mul_f32 v[36:37], v[36:37], v[4:5] op_sel_hi:[1,0]
	v_pk_mul_f32 v[48:49], v[48:49], v[4:5] op_sel_hi:[1,0]
	v_pk_mul_f32 v[52:53], v[148:149], v[30:31]
	v_pk_mul_f32 v[54:55], v[178:179], v[32:33]
	v_pk_mul_f32 v[56:57], v[126:127], v[34:35]
	v_pk_mul_f32 v[58:59], v[150:151], v[6:7]
	v_cvt_pk_f16_f32 v7, v6, v7
	v_cvt_pk_f16_f32 v6, v34, v35
	v_cvt_pk_f16_f32 v5, v32, v33
	v_cvt_pk_f16_f32 v4, v30, v31
	v_pk_mul_f32 v[34:35], v[118:119], v[38:39]
	v_pk_mul_f32 v[60:61], v[120:121], v[50:51]
	v_pk_mul_f32 v[64:65], v[8:9], v[36:37]
	v_pk_mul_f32 v[70:71], v[10:11], v[48:49]
	v_cvt_pk_f16_f32 v11, v48, v49
	v_cvt_pk_f16_f32 v10, v36, v37
	v_cvt_pk_f16_f32 v9, v50, v51
	v_cvt_pk_f16_f32 v8, v38, v39
	v_cvt_pk_f16_f32 v30, v52, v53
	v_cvt_pk_f16_f32 v31, v54, v55
	v_cvt_pk_f16_f32 v32, v56, v57
	v_cvt_pk_f16_f32 v33, v58, v59
	v_cvt_pk_f16_f32 v34, v34, v35
	v_cvt_pk_f16_f32 v35, v60, v61
	v_cvt_pk_f16_f32 v36, v64, v65
	v_cvt_pk_f16_f32 v37, v70, v71
	global_store_dwordx4 v[28:29], v[4:7], off nt
	global_store_dwordx4 v[28:29], v[8:11], off offset:16 nt
	global_store_dwordx4 v[26:27], v[30:33], off nt
	global_store_dwordx4 v[26:27], v[34:37], off offset:16 nt
	s_waitcnt vmcnt(8)
	v_pk_fma_f32 v[4:5], v[154:155], v[12:13], 1.0 op_sel_hi:[1,1,0]
	v_pk_fma_f32 v[6:7], v[182:183], v[14:15], 1.0 op_sel_hi:[1,1,0]
	s_waitcnt vmcnt(7)
	v_pk_fma_f32 v[8:9], v[134:135], v[16:17], 1.0 op_sel_hi:[1,1,0]
	v_pk_fma_f32 v[10:11], v[136:137], v[18:19], 1.0 op_sel_hi:[1,1,0]
	s_waitcnt vmcnt(6)
	v_pk_fma_f32 v[12:13], v[40:41], v[20:21], 1.0 op_sel_hi:[1,1,0]
	v_pk_fma_f32 v[14:15], v[42:43], v[22:23], 1.0 op_sel_hi:[1,1,0]
	v_pk_mul_f32 v[4:5], v[62:63], v[4:5]
	v_pk_mul_f32 v[6:7], v[66:67], v[6:7]
	v_pk_mul_f32 v[8:9], v[68:69], v[8:9]
	v_pk_mul_f32 v[10:11], v[114:115], v[10:11]
	v_pk_mul_f32 v[12:13], v[44:45], v[12:13]
	v_pk_mul_f32 v[14:15], v[46:47], v[14:15]
	v_cvt_pk_f16_f32 v0, v0, v1
	v_cvt_pk_f16_f32 v1, v2, v3
	v_cvt_pk_f16_f32 v2, v4, v5
	v_cvt_pk_f16_f32 v3, v6, v7
	v_cvt_pk_f16_f32 v4, v8, v9
	v_cvt_pk_f16_f32 v5, v10, v11
	v_cvt_pk_f16_f32 v6, v12, v13
	v_cvt_pk_f16_f32 v7, v14, v15
	global_store_dwordx4 v[24:25], v[0:3], off nt
	global_store_dwordx4 v[24:25], v[4:7], off offset:16 nt
	s_waitcnt lgkmcnt(0)
	s_andn2_b64 exec, exec, s[34:35]
	s_cbranch_execnz .LBB0_572
